# QKV projection epilogues (Q, K, V tiles) rewritten by hand: RMS partials reduced cooperatively across the 4 lanes of a row, rope/gain loads issued ahead of stores
# speedup vs baseline: 1.0533x; 1.0075x over previous
.LBB0_637:
	s_cmp_lt_i32 s2, 4
	s_cbranch_scc0 .Lk_epi
	v_lshrrev_b32_e32 v190, 6, v0
	v_and_b32_e32 v192, 15, v0
	v_readfirstlane_b32 s98, v190
	v_bfe_u32 v190, v0, 4, 2
	s_lshl_b32 s100, s24, 8
	s_and_b32 s99, s98, 3
	s_lshr_b32 s98, s98, 2
	s_lshl_b32 s101, s98, 6
	s_add_i32 s100, s100, s101
	v_add_u32_e32 v188, s100, v192
	v_lshlrev_b32_e32 v189, 7, v188
	v_lshl_add_u32 v189, v190, 4, v189
	s_add_u32 s58, s6, 0x10900000
	s_addc_u32 s59, s7, 0
	s_nop 0
	global_load_dwordx4 v[202:205], v189, s[58:59]
	global_load_dwordx4 v[206:209], v189, s[58:59] offset:2048
	s_add_u32 s62, s58, 0x1000
	s_addc_u32 s63, s59, 0
	s_nop 0
	global_load_dwordx4 v[210:213], v189, s[62:63]
	s_add_u32 s62, s58, 0x1800
	s_addc_u32 s63, s59, 0
	s_nop 0
	global_load_dwordx4 v[214:217], v189, s[62:63]
	s_add_u32 s62, s58, 0x4000
	s_addc_u32 s63, s59, 0
	s_nop 0
	global_load_dwordx4 v[218:221], v189, s[62:63]
	s_add_u32 s62, s58, 0x4800
	s_addc_u32 s63, s59, 0
	s_nop 0
	global_load_dwordx4 v[222:225], v189, s[62:63]
	s_add_u32 s62, s58, 0x5000
	s_addc_u32 s63, s59, 0
	s_nop 0
	global_load_dwordx4 v[226:229], v189, s[62:63]
	s_add_u32 s62, s58, 0x5800
	s_addc_u32 s63, s59, 0
	s_nop 0
	global_load_dwordx4 v[162:165], v189, s[62:63]
	v_and_b32_e32 v191, 0xfff, v188
	v_lshlrev_b32_e32 v191, 8, v191
	v_lshl_add_u32 v191, v190, 5, v191
	s_lshl_b32 s100, s2, 9
	s_lshl_b32 s101, s99, 7
	s_add_i32 s100, s100, s101
	v_lshlrev_b32_e32 v192, 11, v188
	v_add_u32_e32 v192, s100, v192
	s_add_u32 s60, s6, 0x8900000
	s_addc_u32 s61, s7, 0
	v_lshl_add_u32 v192, v190, 4, v192
	v_mov_b32_e32 v193, 0x200b8
	ds_read_b64 v[188:189], v193
	v_lshlrev_b32_e32 v194, 5, v190
	s_waitcnt lgkmcnt(0)
	v_readfirstlane_b32 s62, v188
	v_readfirstlane_b32 s63, v189
	v_readlane_b32 s100, v255, 17
	s_nop 3
	s_lshl_b32 s100, s100, 8
	s_add_u32 s62, s62, s100
	s_addc_u32 s63, s63, 0
	s_nop 0
	global_load_dwordx4 v[130:133], v194, s[62:63]
	global_load_dwordx4 v[134:137], v194, s[62:63] offset:16
	global_load_dwordx4 v[138:141], v194, s[62:63] offset:128
	global_load_dwordx4 v[142:145], v194, s[62:63] offset:144
	s_add_u32 s58, s6, 0x5310000
	s_addc_u32 s59, s7, 0
	s_nop 0
	global_load_dwordx4 v[146:149], v191, s[58:59]
	global_load_dwordx4 v[150:153], v191, s[58:59] offset:16
	global_load_dwordx4 v[154:157], v191, s[58:59] offset:128
	global_load_dwordx4 v[158:161], v191, s[58:59] offset:144
	v_and_b32_e32 v193, 63, v0
	v_xor_b32_e32 v194, 32, v193
	v_xor_b32_e32 v193, 16, v193
	v_lshlrev_b32_e32 v193, 2, v193
	v_lshlrev_b32_e32 v194, 2, v194
	v_mov_b32_e32 v188, 0x3a800000
	s_waitcnt vmcnt(8)
	v_add_f32_e32 v202, v202, v203
	v_add_f32_e32 v204, v204, v205
	v_add_f32_e32 v202, v202, v204
	v_add_f32_e32 v206, v206, v207
	v_add_f32_e32 v208, v208, v209
	v_add_f32_e32 v206, v206, v208
	v_add_f32_e32 v210, v210, v211
	v_add_f32_e32 v212, v212, v213
	v_add_f32_e32 v210, v210, v212
	v_add_f32_e32 v214, v214, v215
	v_add_f32_e32 v216, v216, v217
	v_add_f32_e32 v214, v214, v216
	v_add_f32_e32 v218, v218, v219
	v_add_f32_e32 v220, v220, v221
	v_add_f32_e32 v218, v218, v220
	v_add_f32_e32 v222, v222, v223
	v_add_f32_e32 v224, v224, v225
	v_add_f32_e32 v222, v222, v224
	v_add_f32_e32 v226, v226, v227
	v_add_f32_e32 v228, v228, v229
	v_add_f32_e32 v226, v226, v228
	v_add_f32_e32 v162, v162, v163
	v_add_f32_e32 v164, v164, v165
	v_add_f32_e32 v162, v162, v164
	ds_bpermute_b32 v203, v193, v202
	ds_bpermute_b32 v207, v193, v206
	ds_bpermute_b32 v211, v193, v210
	ds_bpermute_b32 v215, v193, v214
	ds_bpermute_b32 v219, v193, v218
	ds_bpermute_b32 v223, v193, v222
	ds_bpermute_b32 v227, v193, v226
	ds_bpermute_b32 v163, v193, v162
	s_waitcnt lgkmcnt(7)
	v_add_f32_e32 v202, v202, v203
	s_waitcnt lgkmcnt(6)
	v_add_f32_e32 v206, v206, v207
	s_waitcnt lgkmcnt(5)
	v_add_f32_e32 v210, v210, v211
	s_waitcnt lgkmcnt(4)
	v_add_f32_e32 v214, v214, v215
	s_waitcnt lgkmcnt(3)
	v_add_f32_e32 v218, v218, v219
	s_waitcnt lgkmcnt(2)
	v_add_f32_e32 v222, v222, v223
	s_waitcnt lgkmcnt(1)
	v_add_f32_e32 v226, v226, v227
	s_waitcnt lgkmcnt(0)
	v_add_f32_e32 v162, v162, v163
	ds_bpermute_b32 v203, v194, v202
	ds_bpermute_b32 v207, v194, v206
	ds_bpermute_b32 v211, v194, v210
	ds_bpermute_b32 v215, v194, v214
	ds_bpermute_b32 v219, v194, v218
	ds_bpermute_b32 v223, v194, v222
	ds_bpermute_b32 v227, v194, v226
	ds_bpermute_b32 v163, v194, v162
	s_waitcnt lgkmcnt(7)
	v_add_f32_e32 v202, v202, v203
	s_waitcnt lgkmcnt(6)
	v_add_f32_e32 v206, v206, v207
	s_waitcnt lgkmcnt(5)
	v_add_f32_e32 v210, v210, v211
	s_waitcnt lgkmcnt(4)
	v_add_f32_e32 v214, v214, v215
	s_waitcnt lgkmcnt(3)
	v_add_f32_e32 v218, v218, v219
	s_waitcnt lgkmcnt(2)
	v_add_f32_e32 v222, v222, v223
	s_waitcnt lgkmcnt(1)
	v_add_f32_e32 v226, v226, v227
	s_waitcnt lgkmcnt(0)
	v_add_f32_e32 v162, v162, v163
	v_fmaak_f32 v202, v188, v202, 0x358637bd
	v_rsq_f32_e32 v230, v202
	v_fmaak_f32 v206, v188, v206, 0x358637bd
	v_rsq_f32_e32 v248, v206
	v_fmaak_f32 v210, v188, v210, 0x358637bd
	v_rsq_f32_e32 v249, v210
	v_fmaak_f32 v214, v188, v214, 0x358637bd
	v_rsq_f32_e32 v250, v214
	v_fmaak_f32 v218, v188, v218, 0x358637bd
	v_rsq_f32_e32 v251, v218
	v_fmaak_f32 v222, v188, v222, 0x358637bd
	v_rsq_f32_e32 v252, v222
	v_fmaak_f32 v226, v188, v226, 0x358637bd
	v_rsq_f32_e32 v253, v226
	v_fmaak_f32 v162, v188, v162, 0x358637bd
	v_rsq_f32_e32 v254, v162
	s_nop 0
	s_add_u32 s62, s58, 0x1000
	s_addc_u32 s63, s59, 0
	s_nop 0
	global_load_dwordx4 v[202:205], v191, s[62:63]
	global_load_dwordx4 v[206:209], v191, s[62:63] offset:16
	global_load_dwordx4 v[210:213], v191, s[62:63] offset:128
	global_load_dwordx4 v[214:217], v191, s[62:63] offset:144
	v_mul_f32_e32 v126, v126, v230
	v_mul_f32_e32 v127, v127, v230
	v_mul_f32_e32 v128, v128, v230
	v_mul_f32_e32 v129, v129, v230
	v_mul_f32_e32 v122, v122, v230
	v_mul_f32_e32 v123, v123, v230
	v_mul_f32_e32 v124, v124, v230
	v_mul_f32_e32 v125, v125, v230
	v_mul_f32_e32 v118, v118, v230
	v_mul_f32_e32 v119, v119, v230
	v_mul_f32_e32 v120, v120, v230
	v_mul_f32_e32 v121, v121, v230
	v_mul_f32_e32 v114, v114, v230
	v_mul_f32_e32 v115, v115, v230
	v_mul_f32_e32 v116, v116, v230
	v_mul_f32_e32 v117, v117, v230
	v_mul_f32_e32 v188, v126, v126
	v_mul_f32_e32 v189, v128, v128
	v_fmac_f32_e32 v188, v127, v127
	v_fmac_f32_e32 v189, v129, v129
	v_add_f32_e32 v230, v188, v189
	v_mul_f32_e32 v188, v122, v122
	v_mul_f32_e32 v189, v124, v124
	v_fmac_f32_e32 v188, v123, v123
	v_fmac_f32_e32 v189, v125, v125
	v_add_f32_e32 v188, v188, v189
	v_add_f32_e32 v230, v230, v188
	v_mul_f32_e32 v188, v118, v118
	v_mul_f32_e32 v189, v120, v120
	v_fmac_f32_e32 v188, v119, v119
	v_fmac_f32_e32 v189, v121, v121
	v_add_f32_e32 v188, v188, v189
	v_add_f32_e32 v230, v230, v188
	v_mul_f32_e32 v188, v114, v114
	v_mul_f32_e32 v189, v116, v116
	v_fmac_f32_e32 v188, v115, v115
	v_fmac_f32_e32 v189, v117, v117
	v_add_f32_e32 v188, v188, v189
	v_add_f32_e32 v230, v230, v188
	v_mul_f32_e32 v110, v110, v248
	v_mul_f32_e32 v111, v111, v248
	v_mul_f32_e32 v112, v112, v248
	v_mul_f32_e32 v113, v113, v248
	v_mul_f32_e32 v106, v106, v248
	v_mul_f32_e32 v107, v107, v248
	v_mul_f32_e32 v108, v108, v248
	v_mul_f32_e32 v109, v109, v248
	v_mul_f32_e32 v102, v102, v248
	v_mul_f32_e32 v103, v103, v248
	v_mul_f32_e32 v104, v104, v248
	v_mul_f32_e32 v105, v105, v248
	v_mul_f32_e32 v98, v98, v248
	v_mul_f32_e32 v99, v99, v248
	v_mul_f32_e32 v100, v100, v248
	v_mul_f32_e32 v101, v101, v248
	v_mul_f32_e32 v188, v110, v110
	v_mul_f32_e32 v189, v112, v112
	v_fmac_f32_e32 v188, v111, v111
	v_fmac_f32_e32 v189, v113, v113
	v_add_f32_e32 v248, v188, v189
	v_mul_f32_e32 v188, v106, v106
	v_mul_f32_e32 v189, v108, v108
	v_fmac_f32_e32 v188, v107, v107
	v_fmac_f32_e32 v189, v109, v109
	v_add_f32_e32 v188, v188, v189
	v_add_f32_e32 v248, v248, v188
	v_mul_f32_e32 v188, v102, v102
	v_mul_f32_e32 v189, v104, v104
	v_fmac_f32_e32 v188, v103, v103
	v_fmac_f32_e32 v189, v105, v105
	v_add_f32_e32 v188, v188, v189
	v_add_f32_e32 v248, v248, v188
	v_mul_f32_e32 v188, v98, v98
	v_mul_f32_e32 v189, v100, v100
	v_fmac_f32_e32 v188, v99, v99
	v_fmac_f32_e32 v189, v101, v101
	v_add_f32_e32 v188, v188, v189
	v_add_f32_e32 v248, v248, v188
	v_mul_f32_e32 v94, v94, v249
	v_mul_f32_e32 v95, v95, v249
	v_mul_f32_e32 v96, v96, v249
	v_mul_f32_e32 v97, v97, v249
	v_mul_f32_e32 v90, v90, v249
	v_mul_f32_e32 v91, v91, v249
	v_mul_f32_e32 v92, v92, v249
	v_mul_f32_e32 v93, v93, v249
	v_mul_f32_e32 v86, v86, v249
	v_mul_f32_e32 v87, v87, v249
	v_mul_f32_e32 v88, v88, v249
	v_mul_f32_e32 v89, v89, v249
	v_mul_f32_e32 v82, v82, v249
	v_mul_f32_e32 v83, v83, v249
	v_mul_f32_e32 v84, v84, v249
	v_mul_f32_e32 v85, v85, v249
	v_mul_f32_e32 v188, v94, v94
	v_mul_f32_e32 v189, v96, v96
	v_fmac_f32_e32 v188, v95, v95
	v_fmac_f32_e32 v189, v97, v97
	v_add_f32_e32 v249, v188, v189
	v_mul_f32_e32 v188, v90, v90
	v_mul_f32_e32 v189, v92, v92
	v_fmac_f32_e32 v188, v91, v91
	v_fmac_f32_e32 v189, v93, v93
	v_add_f32_e32 v188, v188, v189
	v_add_f32_e32 v249, v249, v188
	v_mul_f32_e32 v188, v86, v86
	v_mul_f32_e32 v189, v88, v88
	v_fmac_f32_e32 v188, v87, v87
	v_fmac_f32_e32 v189, v89, v89
	v_add_f32_e32 v188, v188, v189
	v_add_f32_e32 v249, v249, v188
	v_mul_f32_e32 v188, v82, v82
	v_mul_f32_e32 v189, v84, v84
	v_fmac_f32_e32 v188, v83, v83
	v_fmac_f32_e32 v189, v85, v85
	v_add_f32_e32 v188, v188, v189
	v_add_f32_e32 v249, v249, v188
	v_mul_f32_e32 v78, v78, v250
	v_mul_f32_e32 v79, v79, v250
	v_mul_f32_e32 v80, v80, v250
	v_mul_f32_e32 v81, v81, v250
	v_mul_f32_e32 v74, v74, v250
	v_mul_f32_e32 v75, v75, v250
	v_mul_f32_e32 v76, v76, v250
	v_mul_f32_e32 v77, v77, v250
	v_mul_f32_e32 v70, v70, v250
	v_mul_f32_e32 v71, v71, v250
	v_mul_f32_e32 v72, v72, v250
	v_mul_f32_e32 v73, v73, v250
	v_mul_f32_e32 v66, v66, v250
	v_mul_f32_e32 v67, v67, v250
	v_mul_f32_e32 v68, v68, v250
	v_mul_f32_e32 v69, v69, v250
	v_mul_f32_e32 v188, v78, v78
	v_mul_f32_e32 v189, v80, v80
	v_fmac_f32_e32 v188, v79, v79
	v_fmac_f32_e32 v189, v81, v81
	v_add_f32_e32 v250, v188, v189
	v_mul_f32_e32 v188, v74, v74
	v_mul_f32_e32 v189, v76, v76
	v_fmac_f32_e32 v188, v75, v75
	v_fmac_f32_e32 v189, v77, v77
	v_add_f32_e32 v188, v188, v189
	v_add_f32_e32 v250, v250, v188
	v_mul_f32_e32 v188, v70, v70
	v_mul_f32_e32 v189, v72, v72
	v_fmac_f32_e32 v188, v71, v71
	v_fmac_f32_e32 v189, v73, v73
	v_add_f32_e32 v188, v188, v189
	v_add_f32_e32 v250, v250, v188
	v_mul_f32_e32 v188, v66, v66
	v_mul_f32_e32 v189, v68, v68
	v_fmac_f32_e32 v188, v67, v67
	v_fmac_f32_e32 v189, v69, v69
	v_add_f32_e32 v188, v188, v189
	v_add_f32_e32 v250, v250, v188
	v_mul_f32_e32 v62, v62, v251
	v_mul_f32_e32 v63, v63, v251
	v_mul_f32_e32 v64, v64, v251
	v_mul_f32_e32 v65, v65, v251
	v_mul_f32_e32 v58, v58, v251
	v_mul_f32_e32 v59, v59, v251
	v_mul_f32_e32 v60, v60, v251
	v_mul_f32_e32 v61, v61, v251
	v_mul_f32_e32 v54, v54, v251
	v_mul_f32_e32 v55, v55, v251
	v_mul_f32_e32 v56, v56, v251
	v_mul_f32_e32 v57, v57, v251
	v_mul_f32_e32 v50, v50, v251
	v_mul_f32_e32 v51, v51, v251
	v_mul_f32_e32 v52, v52, v251
	v_mul_f32_e32 v53, v53, v251
	v_mul_f32_e32 v188, v62, v62
	v_mul_f32_e32 v189, v64, v64
	v_fmac_f32_e32 v188, v63, v63
	v_fmac_f32_e32 v189, v65, v65
	v_add_f32_e32 v251, v188, v189
	v_mul_f32_e32 v188, v58, v58
	v_mul_f32_e32 v189, v60, v60
	v_fmac_f32_e32 v188, v59, v59
	v_fmac_f32_e32 v189, v61, v61
	v_add_f32_e32 v188, v188, v189
	v_add_f32_e32 v251, v251, v188
	v_mul_f32_e32 v188, v54, v54
	v_mul_f32_e32 v189, v56, v56
	v_fmac_f32_e32 v188, v55, v55
	v_fmac_f32_e32 v189, v57, v57
	v_add_f32_e32 v188, v188, v189
	v_add_f32_e32 v251, v251, v188
	v_mul_f32_e32 v188, v50, v50
	v_mul_f32_e32 v189, v52, v52
	v_fmac_f32_e32 v188, v51, v51
	v_fmac_f32_e32 v189, v53, v53
	v_add_f32_e32 v188, v188, v189
	v_add_f32_e32 v251, v251, v188
	v_mul_f32_e32 v46, v46, v252
	v_mul_f32_e32 v47, v47, v252
	v_mul_f32_e32 v48, v48, v252
	v_mul_f32_e32 v49, v49, v252
	v_mul_f32_e32 v42, v42, v252
	v_mul_f32_e32 v43, v43, v252
	v_mul_f32_e32 v44, v44, v252
	v_mul_f32_e32 v45, v45, v252
	v_mul_f32_e32 v38, v38, v252
	v_mul_f32_e32 v39, v39, v252
	v_mul_f32_e32 v40, v40, v252
	v_mul_f32_e32 v41, v41, v252
	v_mul_f32_e32 v34, v34, v252
	v_mul_f32_e32 v35, v35, v252
	v_mul_f32_e32 v36, v36, v252
	v_mul_f32_e32 v37, v37, v252
	v_mul_f32_e32 v188, v46, v46
	v_mul_f32_e32 v189, v48, v48
	v_fmac_f32_e32 v188, v47, v47
	v_fmac_f32_e32 v189, v49, v49
	v_add_f32_e32 v252, v188, v189
	v_mul_f32_e32 v188, v42, v42
	v_mul_f32_e32 v189, v44, v44
	v_fmac_f32_e32 v188, v43, v43
	v_fmac_f32_e32 v189, v45, v45
	v_add_f32_e32 v188, v188, v189
	v_add_f32_e32 v252, v252, v188
	v_mul_f32_e32 v188, v38, v38
	v_mul_f32_e32 v189, v40, v40
	v_fmac_f32_e32 v188, v39, v39
	v_fmac_f32_e32 v189, v41, v41
	v_add_f32_e32 v188, v188, v189
	v_add_f32_e32 v252, v252, v188
	v_mul_f32_e32 v188, v34, v34
	v_mul_f32_e32 v189, v36, v36
	v_fmac_f32_e32 v188, v35, v35
	v_fmac_f32_e32 v189, v37, v37
	v_add_f32_e32 v188, v188, v189
	v_add_f32_e32 v252, v252, v188
	v_mul_f32_e32 v30, v30, v253
	v_mul_f32_e32 v31, v31, v253
	v_mul_f32_e32 v32, v32, v253
	v_mul_f32_e32 v33, v33, v253
	v_mul_f32_e32 v26, v26, v253
	v_mul_f32_e32 v27, v27, v253
	v_mul_f32_e32 v28, v28, v253
	v_mul_f32_e32 v29, v29, v253
	v_mul_f32_e32 v22, v22, v253
	v_mul_f32_e32 v23, v23, v253
	v_mul_f32_e32 v24, v24, v253
	v_mul_f32_e32 v25, v25, v253
	v_mul_f32_e32 v18, v18, v253
	v_mul_f32_e32 v19, v19, v253
	v_mul_f32_e32 v20, v20, v253
	v_mul_f32_e32 v21, v21, v253
	v_mul_f32_e32 v188, v30, v30
	v_mul_f32_e32 v189, v32, v32
	v_fmac_f32_e32 v188, v31, v31
	v_fmac_f32_e32 v189, v33, v33
	v_add_f32_e32 v253, v188, v189
	v_mul_f32_e32 v188, v26, v26
	v_mul_f32_e32 v189, v28, v28
	v_fmac_f32_e32 v188, v27, v27
	v_fmac_f32_e32 v189, v29, v29
	v_add_f32_e32 v188, v188, v189
	v_add_f32_e32 v253, v253, v188
	v_mul_f32_e32 v188, v22, v22
	v_mul_f32_e32 v189, v24, v24
	v_fmac_f32_e32 v188, v23, v23
	v_fmac_f32_e32 v189, v25, v25
	v_add_f32_e32 v188, v188, v189
	v_add_f32_e32 v253, v253, v188
	v_mul_f32_e32 v188, v18, v18
	v_mul_f32_e32 v189, v20, v20
	v_fmac_f32_e32 v188, v19, v19
	v_fmac_f32_e32 v189, v21, v21
	v_add_f32_e32 v188, v188, v189
	v_add_f32_e32 v253, v253, v188
	v_mul_f32_e32 v14, v14, v254
	v_mul_f32_e32 v15, v15, v254
	v_mul_f32_e32 v16, v16, v254
	v_mul_f32_e32 v17, v17, v254
	v_mul_f32_e32 v10, v10, v254
	v_mul_f32_e32 v11, v11, v254
	v_mul_f32_e32 v12, v12, v254
	v_mul_f32_e32 v13, v13, v254
	v_mul_f32_e32 v6, v6, v254
	v_mul_f32_e32 v7, v7, v254
	v_mul_f32_e32 v8, v8, v254
	v_mul_f32_e32 v9, v9, v254
	v_mul_f32_e32 v2, v2, v254
	v_mul_f32_e32 v3, v3, v254
	v_mul_f32_e32 v4, v4, v254
	v_mul_f32_e32 v5, v5, v254
	v_mul_f32_e32 v188, v14, v14
	v_mul_f32_e32 v189, v16, v16
	v_fmac_f32_e32 v188, v15, v15
	v_fmac_f32_e32 v189, v17, v17
	v_add_f32_e32 v254, v188, v189
	v_mul_f32_e32 v188, v10, v10
	v_mul_f32_e32 v189, v12, v12
	v_fmac_f32_e32 v188, v11, v11
	v_fmac_f32_e32 v189, v13, v13
	v_add_f32_e32 v188, v188, v189
	v_add_f32_e32 v254, v254, v188
	v_mul_f32_e32 v188, v6, v6
	v_mul_f32_e32 v189, v8, v8
	v_fmac_f32_e32 v188, v7, v7
	v_fmac_f32_e32 v189, v9, v9
	v_add_f32_e32 v188, v188, v189
	v_add_f32_e32 v254, v254, v188
	v_mul_f32_e32 v188, v2, v2
	v_mul_f32_e32 v189, v4, v4
	v_fmac_f32_e32 v188, v3, v3
	v_fmac_f32_e32 v189, v5, v5
	v_add_f32_e32 v188, v188, v189
	v_add_f32_e32 v254, v254, v188
	ds_bpermute_b32 v218, v193, v230
	ds_bpermute_b32 v219, v193, v248
	ds_bpermute_b32 v220, v193, v249
	ds_bpermute_b32 v221, v193, v250
	ds_bpermute_b32 v222, v193, v251
	ds_bpermute_b32 v223, v193, v252
	ds_bpermute_b32 v224, v193, v253
	ds_bpermute_b32 v225, v193, v254
	s_waitcnt lgkmcnt(7)
	v_add_f32_e32 v230, v230, v218
	s_waitcnt lgkmcnt(6)
	v_add_f32_e32 v248, v248, v219
	s_waitcnt lgkmcnt(5)
	v_add_f32_e32 v249, v249, v220
	s_waitcnt lgkmcnt(4)
	v_add_f32_e32 v250, v250, v221
	s_waitcnt lgkmcnt(3)
	v_add_f32_e32 v251, v251, v222
	s_waitcnt lgkmcnt(2)
	v_add_f32_e32 v252, v252, v223
	s_waitcnt lgkmcnt(1)
	v_add_f32_e32 v253, v253, v224
	s_waitcnt lgkmcnt(0)
	v_add_f32_e32 v254, v254, v225
	ds_bpermute_b32 v218, v194, v230
	ds_bpermute_b32 v219, v194, v248
	ds_bpermute_b32 v220, v194, v249
	ds_bpermute_b32 v221, v194, v250
	ds_bpermute_b32 v222, v194, v251
	ds_bpermute_b32 v223, v194, v252
	ds_bpermute_b32 v224, v194, v253
	ds_bpermute_b32 v225, v194, v254
	s_waitcnt lgkmcnt(7)
	v_add_f32_e32 v230, v230, v218
	s_waitcnt lgkmcnt(6)
	v_add_f32_e32 v248, v248, v219
	s_waitcnt lgkmcnt(5)
	v_add_f32_e32 v249, v249, v220
	s_waitcnt lgkmcnt(4)
	v_add_f32_e32 v250, v250, v221
	s_waitcnt lgkmcnt(3)
	v_add_f32_e32 v251, v251, v222
	s_waitcnt lgkmcnt(2)
	v_add_f32_e32 v252, v252, v223
	s_waitcnt lgkmcnt(1)
	v_add_f32_e32 v253, v253, v224
	s_waitcnt lgkmcnt(0)
	v_add_f32_e32 v254, v254, v225
	v_mov_b32_e32 v188, 0x3c800000
	v_fmaak_f32 v230, v188, v230, 0x358637bd
	v_rsq_f32_e32 v230, v230
	v_fmaak_f32 v248, v188, v248, 0x358637bd
	v_rsq_f32_e32 v248, v248
	v_fmaak_f32 v249, v188, v249, 0x358637bd
	v_rsq_f32_e32 v249, v249
	v_fmaak_f32 v250, v188, v250, 0x358637bd
	v_rsq_f32_e32 v250, v250
	v_fmaak_f32 v251, v188, v251, 0x358637bd
	v_rsq_f32_e32 v251, v251
	v_fmaak_f32 v252, v188, v252, 0x358637bd
	v_rsq_f32_e32 v252, v252
	v_fmaak_f32 v253, v188, v253, 0x358637bd
	v_rsq_f32_e32 v253, v253
	v_fmaak_f32 v254, v188, v254, 0x358637bd
	v_rsq_f32_e32 v254, v254
	s_nop 0
	s_add_u32 s62, s58, 0x2000
	s_addc_u32 s63, s59, 0
	s_nop 0
	global_load_dwordx4 v[218:221], v191, s[62:63]
	global_load_dwordx4 v[222:225], v191, s[62:63] offset:16
	global_load_dwordx4 v[226:229], v191, s[62:63] offset:128
	global_load_dwordx4 v[162:165], v191, s[62:63] offset:144
	s_waitcnt vmcnt(12)
	s_mov_b32 s100, 0x3e38aa3b
	v_mul_f32_e32 v130, s100, v130
	v_mul_f32_e32 v131, s100, v131
	v_mul_f32_e32 v132, s100, v132
	v_mul_f32_e32 v133, s100, v133
	v_mul_f32_e32 v134, s100, v134
	v_mul_f32_e32 v135, s100, v135
	v_mul_f32_e32 v136, s100, v136
	v_mul_f32_e32 v137, s100, v137
	v_mul_f32_e32 v138, s100, v138
	v_mul_f32_e32 v139, s100, v139
	v_mul_f32_e32 v140, s100, v140
	v_mul_f32_e32 v141, s100, v141
	v_mul_f32_e32 v142, s100, v142
	v_mul_f32_e32 v143, s100, v143
	v_mul_f32_e32 v144, s100, v144
	v_mul_f32_e32 v145, s100, v145
	v_mul_f32_e32 v126, v126, v230
	v_mul_f32_e32 v127, v127, v230
	v_mul_f32_e32 v128, v128, v230
	v_mul_f32_e32 v129, v129, v230
	v_mul_f32_e32 v122, v122, v230
	v_mul_f32_e32 v123, v123, v230
	v_mul_f32_e32 v124, v124, v230
	v_mul_f32_e32 v125, v125, v230
	v_mul_f32_e32 v118, v118, v230
	v_mul_f32_e32 v119, v119, v230
	v_mul_f32_e32 v120, v120, v230
	v_mul_f32_e32 v121, v121, v230
	v_mul_f32_e32 v114, v114, v230
	v_mul_f32_e32 v115, v115, v230
	v_mul_f32_e32 v116, v116, v230
	v_mul_f32_e32 v117, v117, v230
	v_pk_mul_f32 v[126:127], v[126:127], v[130:131]
	v_pk_mul_f32 v[118:119], v[118:119], v[138:139]
	v_pk_mul_f32 v[128:129], v[128:129], v[132:133]
	v_pk_mul_f32 v[120:121], v[120:121], v[140:141]
	v_pk_mul_f32 v[122:123], v[122:123], v[134:135]
	v_pk_mul_f32 v[114:115], v[114:115], v[142:143]
	v_pk_mul_f32 v[124:125], v[124:125], v[136:137]
	v_pk_mul_f32 v[116:117], v[116:117], v[144:145]
	s_waitcnt vmcnt(8)
	v_pk_mul_f32 v[188:189], v[118:119], v[154:155]
	v_pk_mul_f32 v[118:119], v[118:119], v[146:147]
	v_pk_fma_f32 v[146:147], v[126:127], v[146:147], v[188:189] neg_lo:[0,0,1] neg_hi:[0,0,1]
	v_pk_fma_f32 v[154:155], v[126:127], v[154:155], v[118:119]
	v_pk_mul_f32 v[188:189], v[120:121], v[156:157]
	v_pk_mul_f32 v[120:121], v[120:121], v[148:149]
	v_pk_fma_f32 v[148:149], v[128:129], v[148:149], v[188:189] neg_lo:[0,0,1] neg_hi:[0,0,1]
	v_pk_fma_f32 v[156:157], v[128:129], v[156:157], v[120:121]
	v_pk_mul_f32 v[188:189], v[114:115], v[158:159]
	v_pk_mul_f32 v[114:115], v[114:115], v[150:151]
	v_pk_fma_f32 v[150:151], v[122:123], v[150:151], v[188:189] neg_lo:[0,0,1] neg_hi:[0,0,1]
	v_pk_fma_f32 v[158:159], v[122:123], v[158:159], v[114:115]
	v_pk_mul_f32 v[188:189], v[116:117], v[160:161]
	v_pk_mul_f32 v[116:117], v[116:117], v[152:153]
	v_pk_fma_f32 v[152:153], v[124:125], v[152:153], v[188:189] neg_lo:[0,0,1] neg_hi:[0,0,1]
	v_pk_fma_f32 v[160:161], v[124:125], v[160:161], v[116:117]
	v_cvt_pk_bf16_f32 v126, v146, v147
	v_cvt_pk_bf16_f32 v127, v148, v149
	v_cvt_pk_bf16_f32 v128, v150, v151
	v_cvt_pk_bf16_f32 v129, v152, v153
	v_cvt_pk_bf16_f32 v122, v154, v155
	v_cvt_pk_bf16_f32 v123, v156, v157
	v_cvt_pk_bf16_f32 v124, v158, v159
	v_cvt_pk_bf16_f32 v125, v160, v161
	s_add_u32 s62, s58, 0x3000
	s_addc_u32 s63, s59, 0
	s_nop 0
	global_load_dwordx4 v[146:149], v191, s[62:63]
	global_load_dwordx4 v[150:153], v191, s[62:63] offset:16
	global_load_dwordx4 v[154:157], v191, s[62:63] offset:128
	global_load_dwordx4 v[158:161], v191, s[62:63] offset:144
	s_nop 0
	global_store_dwordx4 v192, v[126:129], s[60:61]
	global_store_dwordx4 v192, v[122:125], s[60:61] offset:64
	v_mul_f32_e32 v110, v110, v248
	v_mul_f32_e32 v111, v111, v248
	v_mul_f32_e32 v112, v112, v248
	v_mul_f32_e32 v113, v113, v248
	v_mul_f32_e32 v106, v106, v248
	v_mul_f32_e32 v107, v107, v248
	v_mul_f32_e32 v108, v108, v248
	v_mul_f32_e32 v109, v109, v248
	v_mul_f32_e32 v102, v102, v248
	v_mul_f32_e32 v103, v103, v248
	v_mul_f32_e32 v104, v104, v248
	v_mul_f32_e32 v105, v105, v248
	v_mul_f32_e32 v98, v98, v248
	v_mul_f32_e32 v99, v99, v248
	v_mul_f32_e32 v100, v100, v248
	v_mul_f32_e32 v101, v101, v248
	v_pk_mul_f32 v[110:111], v[110:111], v[130:131]
	v_pk_mul_f32 v[102:103], v[102:103], v[138:139]
	v_pk_mul_f32 v[112:113], v[112:113], v[132:133]
	v_pk_mul_f32 v[104:105], v[104:105], v[140:141]
	v_pk_mul_f32 v[106:107], v[106:107], v[134:135]
	v_pk_mul_f32 v[98:99], v[98:99], v[142:143]
	v_pk_mul_f32 v[108:109], v[108:109], v[136:137]
	v_pk_mul_f32 v[100:101], v[100:101], v[144:145]
	s_waitcnt vmcnt(10)
	v_pk_mul_f32 v[188:189], v[102:103], v[210:211]
	v_pk_mul_f32 v[102:103], v[102:103], v[202:203]
	v_pk_fma_f32 v[202:203], v[110:111], v[202:203], v[188:189] neg_lo:[0,0,1] neg_hi:[0,0,1]
	v_pk_fma_f32 v[210:211], v[110:111], v[210:211], v[102:103]
	v_pk_mul_f32 v[188:189], v[104:105], v[212:213]
	v_pk_mul_f32 v[104:105], v[104:105], v[204:205]
	v_pk_fma_f32 v[204:205], v[112:113], v[204:205], v[188:189] neg_lo:[0,0,1] neg_hi:[0,0,1]
	v_pk_fma_f32 v[212:213], v[112:113], v[212:213], v[104:105]
	v_pk_mul_f32 v[188:189], v[98:99], v[214:215]
	v_pk_mul_f32 v[98:99], v[98:99], v[206:207]
	v_pk_fma_f32 v[206:207], v[106:107], v[206:207], v[188:189] neg_lo:[0,0,1] neg_hi:[0,0,1]
	v_pk_fma_f32 v[214:215], v[106:107], v[214:215], v[98:99]
	v_pk_mul_f32 v[188:189], v[100:101], v[216:217]
	v_pk_mul_f32 v[100:101], v[100:101], v[208:209]
	v_pk_fma_f32 v[208:209], v[108:109], v[208:209], v[188:189] neg_lo:[0,0,1] neg_hi:[0,0,1]
	v_pk_fma_f32 v[216:217], v[108:109], v[216:217], v[100:101]
	v_cvt_pk_bf16_f32 v110, v202, v203
	v_cvt_pk_bf16_f32 v111, v204, v205
	v_cvt_pk_bf16_f32 v112, v206, v207
	v_cvt_pk_bf16_f32 v113, v208, v209
	v_cvt_pk_bf16_f32 v106, v210, v211
	v_cvt_pk_bf16_f32 v107, v212, v213
	v_cvt_pk_bf16_f32 v108, v214, v215
	v_cvt_pk_bf16_f32 v109, v216, v217
	s_add_u32 s62, s58, 0x8000
	s_addc_u32 s63, s59, 0
	s_nop 0
	global_load_dwordx4 v[202:205], v191, s[62:63]
	global_load_dwordx4 v[206:209], v191, s[62:63] offset:16
	global_load_dwordx4 v[210:213], v191, s[62:63] offset:128
	global_load_dwordx4 v[214:217], v191, s[62:63] offset:144
	s_add_u32 s62, s60, 0x8000
	s_addc_u32 s63, s61, 0
	s_nop 0
	global_store_dwordx4 v192, v[110:113], s[62:63]
	global_store_dwordx4 v192, v[106:109], s[62:63] offset:64
	v_mul_f32_e32 v94, v94, v249
	v_mul_f32_e32 v95, v95, v249
	v_mul_f32_e32 v96, v96, v249
	v_mul_f32_e32 v97, v97, v249
	v_mul_f32_e32 v90, v90, v249
	v_mul_f32_e32 v91, v91, v249
	v_mul_f32_e32 v92, v92, v249
	v_mul_f32_e32 v93, v93, v249
	v_mul_f32_e32 v86, v86, v249
	v_mul_f32_e32 v87, v87, v249
	v_mul_f32_e32 v88, v88, v249
	v_mul_f32_e32 v89, v89, v249
	v_mul_f32_e32 v82, v82, v249
	v_mul_f32_e32 v83, v83, v249
	v_mul_f32_e32 v84, v84, v249
	v_mul_f32_e32 v85, v85, v249
	v_pk_mul_f32 v[94:95], v[94:95], v[130:131]
	v_pk_mul_f32 v[86:87], v[86:87], v[138:139]
	v_pk_mul_f32 v[96:97], v[96:97], v[132:133]
	v_pk_mul_f32 v[88:89], v[88:89], v[140:141]
	v_pk_mul_f32 v[90:91], v[90:91], v[134:135]
	v_pk_mul_f32 v[82:83], v[82:83], v[142:143]
	v_pk_mul_f32 v[92:93], v[92:93], v[136:137]
	v_pk_mul_f32 v[84:85], v[84:85], v[144:145]
	s_waitcnt vmcnt(12)
	v_pk_mul_f32 v[188:189], v[86:87], v[226:227]
	v_pk_mul_f32 v[86:87], v[86:87], v[218:219]
	v_pk_fma_f32 v[218:219], v[94:95], v[218:219], v[188:189] neg_lo:[0,0,1] neg_hi:[0,0,1]
	v_pk_fma_f32 v[226:227], v[94:95], v[226:227], v[86:87]
	v_pk_mul_f32 v[188:189], v[88:89], v[228:229]
	v_pk_mul_f32 v[88:89], v[88:89], v[220:221]
	v_pk_fma_f32 v[220:221], v[96:97], v[220:221], v[188:189] neg_lo:[0,0,1] neg_hi:[0,0,1]
	v_pk_fma_f32 v[228:229], v[96:97], v[228:229], v[88:89]
	v_pk_mul_f32 v[188:189], v[82:83], v[162:163]
	v_pk_mul_f32 v[82:83], v[82:83], v[222:223]
	v_pk_fma_f32 v[222:223], v[90:91], v[222:223], v[188:189] neg_lo:[0,0,1] neg_hi:[0,0,1]
	v_pk_fma_f32 v[162:163], v[90:91], v[162:163], v[82:83]
	v_pk_mul_f32 v[188:189], v[84:85], v[164:165]
	v_pk_mul_f32 v[84:85], v[84:85], v[224:225]
	v_pk_fma_f32 v[224:225], v[92:93], v[224:225], v[188:189] neg_lo:[0,0,1] neg_hi:[0,0,1]
	v_pk_fma_f32 v[164:165], v[92:93], v[164:165], v[84:85]
	v_cvt_pk_bf16_f32 v94, v218, v219
	v_cvt_pk_bf16_f32 v95, v220, v221
	v_cvt_pk_bf16_f32 v96, v222, v223
	v_cvt_pk_bf16_f32 v97, v224, v225
	v_cvt_pk_bf16_f32 v90, v226, v227
	v_cvt_pk_bf16_f32 v91, v228, v229
	v_cvt_pk_bf16_f32 v92, v162, v163
	v_cvt_pk_bf16_f32 v93, v164, v165
	s_add_u32 s62, s58, 0x9000
	s_addc_u32 s63, s59, 0
	s_nop 0
	global_load_dwordx4 v[218:221], v191, s[62:63]
	global_load_dwordx4 v[222:225], v191, s[62:63] offset:16
	global_load_dwordx4 v[226:229], v191, s[62:63] offset:128
	global_load_dwordx4 v[162:165], v191, s[62:63] offset:144
	s_add_u32 s62, s60, 0x10000
	s_addc_u32 s63, s61, 0
	s_nop 0
	global_store_dwordx4 v192, v[94:97], s[62:63]
	global_store_dwordx4 v192, v[90:93], s[62:63] offset:64
	v_mul_f32_e32 v78, v78, v250
	v_mul_f32_e32 v79, v79, v250
	v_mul_f32_e32 v80, v80, v250
	v_mul_f32_e32 v81, v81, v250
	v_mul_f32_e32 v74, v74, v250
	v_mul_f32_e32 v75, v75, v250
	v_mul_f32_e32 v76, v76, v250
	v_mul_f32_e32 v77, v77, v250
	v_mul_f32_e32 v70, v70, v250
	v_mul_f32_e32 v71, v71, v250
	v_mul_f32_e32 v72, v72, v250
	v_mul_f32_e32 v73, v73, v250
	v_mul_f32_e32 v66, v66, v250
	v_mul_f32_e32 v67, v67, v250
	v_mul_f32_e32 v68, v68, v250
	v_mul_f32_e32 v69, v69, v250
	v_pk_mul_f32 v[78:79], v[78:79], v[130:131]
	v_pk_mul_f32 v[70:71], v[70:71], v[138:139]
	v_pk_mul_f32 v[80:81], v[80:81], v[132:133]
	v_pk_mul_f32 v[72:73], v[72:73], v[140:141]
	v_pk_mul_f32 v[74:75], v[74:75], v[134:135]
	v_pk_mul_f32 v[66:67], v[66:67], v[142:143]
	v_pk_mul_f32 v[76:77], v[76:77], v[136:137]
	v_pk_mul_f32 v[68:69], v[68:69], v[144:145]
	s_waitcnt vmcnt(14)
	v_pk_mul_f32 v[188:189], v[70:71], v[154:155]
	v_pk_mul_f32 v[70:71], v[70:71], v[146:147]
	v_pk_fma_f32 v[146:147], v[78:79], v[146:147], v[188:189] neg_lo:[0,0,1] neg_hi:[0,0,1]
	v_pk_fma_f32 v[154:155], v[78:79], v[154:155], v[70:71]
	v_pk_mul_f32 v[188:189], v[72:73], v[156:157]
	v_pk_mul_f32 v[72:73], v[72:73], v[148:149]
	v_pk_fma_f32 v[148:149], v[80:81], v[148:149], v[188:189] neg_lo:[0,0,1] neg_hi:[0,0,1]
	v_pk_fma_f32 v[156:157], v[80:81], v[156:157], v[72:73]
	v_pk_mul_f32 v[188:189], v[66:67], v[158:159]
	v_pk_mul_f32 v[66:67], v[66:67], v[150:151]
	v_pk_fma_f32 v[150:151], v[74:75], v[150:151], v[188:189] neg_lo:[0,0,1] neg_hi:[0,0,1]
	v_pk_fma_f32 v[158:159], v[74:75], v[158:159], v[66:67]
	v_pk_mul_f32 v[188:189], v[68:69], v[160:161]
	v_pk_mul_f32 v[68:69], v[68:69], v[152:153]
	v_pk_fma_f32 v[152:153], v[76:77], v[152:153], v[188:189] neg_lo:[0,0,1] neg_hi:[0,0,1]
	v_pk_fma_f32 v[160:161], v[76:77], v[160:161], v[68:69]
	v_cvt_pk_bf16_f32 v78, v146, v147
	v_cvt_pk_bf16_f32 v79, v148, v149
	v_cvt_pk_bf16_f32 v80, v150, v151
	v_cvt_pk_bf16_f32 v81, v152, v153
	v_cvt_pk_bf16_f32 v74, v154, v155
	v_cvt_pk_bf16_f32 v75, v156, v157
	v_cvt_pk_bf16_f32 v76, v158, v159
	v_cvt_pk_bf16_f32 v77, v160, v161
	s_add_u32 s62, s58, 0xa000
	s_addc_u32 s63, s59, 0
	s_nop 0
	global_load_dwordx4 v[146:149], v191, s[62:63]
	global_load_dwordx4 v[150:153], v191, s[62:63] offset:16
	global_load_dwordx4 v[154:157], v191, s[62:63] offset:128
	global_load_dwordx4 v[158:161], v191, s[62:63] offset:144
	s_add_u32 s62, s60, 0x18000
	s_addc_u32 s63, s61, 0
	s_nop 0
	global_store_dwordx4 v192, v[78:81], s[62:63]
	global_store_dwordx4 v192, v[74:77], s[62:63] offset:64
	v_mul_f32_e32 v62, v62, v251
	v_mul_f32_e32 v63, v63, v251
	v_mul_f32_e32 v64, v64, v251
	v_mul_f32_e32 v65, v65, v251
	v_mul_f32_e32 v58, v58, v251
	v_mul_f32_e32 v59, v59, v251
	v_mul_f32_e32 v60, v60, v251
	v_mul_f32_e32 v61, v61, v251
	v_mul_f32_e32 v54, v54, v251
	v_mul_f32_e32 v55, v55, v251
	v_mul_f32_e32 v56, v56, v251
	v_mul_f32_e32 v57, v57, v251
	v_mul_f32_e32 v50, v50, v251
	v_mul_f32_e32 v51, v51, v251
	v_mul_f32_e32 v52, v52, v251
	v_mul_f32_e32 v53, v53, v251
	v_pk_mul_f32 v[62:63], v[62:63], v[130:131]
	v_pk_mul_f32 v[54:55], v[54:55], v[138:139]
	v_pk_mul_f32 v[64:65], v[64:65], v[132:133]
	v_pk_mul_f32 v[56:57], v[56:57], v[140:141]
	v_pk_mul_f32 v[58:59], v[58:59], v[134:135]
	v_pk_mul_f32 v[50:51], v[50:51], v[142:143]
	v_pk_mul_f32 v[60:61], v[60:61], v[136:137]
	v_pk_mul_f32 v[52:53], v[52:53], v[144:145]
	s_waitcnt vmcnt(14)
	v_pk_mul_f32 v[188:189], v[54:55], v[210:211]
	v_pk_mul_f32 v[54:55], v[54:55], v[202:203]
	v_pk_fma_f32 v[202:203], v[62:63], v[202:203], v[188:189] neg_lo:[0,0,1] neg_hi:[0,0,1]
	v_pk_fma_f32 v[210:211], v[62:63], v[210:211], v[54:55]
	v_pk_mul_f32 v[188:189], v[56:57], v[212:213]
	v_pk_mul_f32 v[56:57], v[56:57], v[204:205]
	v_pk_fma_f32 v[204:205], v[64:65], v[204:205], v[188:189] neg_lo:[0,0,1] neg_hi:[0,0,1]
	v_pk_fma_f32 v[212:213], v[64:65], v[212:213], v[56:57]
	v_pk_mul_f32 v[188:189], v[50:51], v[214:215]
	v_pk_mul_f32 v[50:51], v[50:51], v[206:207]
	v_pk_fma_f32 v[206:207], v[58:59], v[206:207], v[188:189] neg_lo:[0,0,1] neg_hi:[0,0,1]
	v_pk_fma_f32 v[214:215], v[58:59], v[214:215], v[50:51]
	v_pk_mul_f32 v[188:189], v[52:53], v[216:217]
	v_pk_mul_f32 v[52:53], v[52:53], v[208:209]
	v_pk_fma_f32 v[208:209], v[60:61], v[208:209], v[188:189] neg_lo:[0,0,1] neg_hi:[0,0,1]
	v_pk_fma_f32 v[216:217], v[60:61], v[216:217], v[52:53]
	v_cvt_pk_bf16_f32 v62, v202, v203
	v_cvt_pk_bf16_f32 v63, v204, v205
	v_cvt_pk_bf16_f32 v64, v206, v207
	v_cvt_pk_bf16_f32 v65, v208, v209
	v_cvt_pk_bf16_f32 v58, v210, v211
	v_cvt_pk_bf16_f32 v59, v212, v213
	v_cvt_pk_bf16_f32 v60, v214, v215
	v_cvt_pk_bf16_f32 v61, v216, v217
	s_add_u32 s62, s58, 0xb000
	s_addc_u32 s63, s59, 0
	s_nop 0
	global_load_dwordx4 v[202:205], v191, s[62:63]
	global_load_dwordx4 v[206:209], v191, s[62:63] offset:16
	global_load_dwordx4 v[210:213], v191, s[62:63] offset:128
	global_load_dwordx4 v[214:217], v191, s[62:63] offset:144
	s_add_u32 s62, s60, 0x40000
	s_addc_u32 s63, s61, 0
	s_nop 0
	global_store_dwordx4 v192, v[62:65], s[62:63]
	global_store_dwordx4 v192, v[58:61], s[62:63] offset:64
	v_mul_f32_e32 v46, v46, v252
	v_mul_f32_e32 v47, v47, v252
	v_mul_f32_e32 v48, v48, v252
	v_mul_f32_e32 v49, v49, v252
	v_mul_f32_e32 v42, v42, v252
	v_mul_f32_e32 v43, v43, v252
	v_mul_f32_e32 v44, v44, v252
	v_mul_f32_e32 v45, v45, v252
	v_mul_f32_e32 v38, v38, v252
	v_mul_f32_e32 v39, v39, v252
	v_mul_f32_e32 v40, v40, v252
	v_mul_f32_e32 v41, v41, v252
	v_mul_f32_e32 v34, v34, v252
	v_mul_f32_e32 v35, v35, v252
	v_mul_f32_e32 v36, v36, v252
	v_mul_f32_e32 v37, v37, v252
	v_pk_mul_f32 v[46:47], v[46:47], v[130:131]
	v_pk_mul_f32 v[38:39], v[38:39], v[138:139]
	v_pk_mul_f32 v[48:49], v[48:49], v[132:133]
	v_pk_mul_f32 v[40:41], v[40:41], v[140:141]
	v_pk_mul_f32 v[42:43], v[42:43], v[134:135]
	v_pk_mul_f32 v[34:35], v[34:35], v[142:143]
	v_pk_mul_f32 v[44:45], v[44:45], v[136:137]
	v_pk_mul_f32 v[36:37], v[36:37], v[144:145]
	s_waitcnt vmcnt(14)
	v_pk_mul_f32 v[188:189], v[38:39], v[226:227]
	v_pk_mul_f32 v[38:39], v[38:39], v[218:219]
	v_pk_fma_f32 v[218:219], v[46:47], v[218:219], v[188:189] neg_lo:[0,0,1] neg_hi:[0,0,1]
	v_pk_fma_f32 v[226:227], v[46:47], v[226:227], v[38:39]
	v_pk_mul_f32 v[188:189], v[40:41], v[228:229]
	v_pk_mul_f32 v[40:41], v[40:41], v[220:221]
	v_pk_fma_f32 v[220:221], v[48:49], v[220:221], v[188:189] neg_lo:[0,0,1] neg_hi:[0,0,1]
	v_pk_fma_f32 v[228:229], v[48:49], v[228:229], v[40:41]
	v_pk_mul_f32 v[188:189], v[34:35], v[162:163]
	v_pk_mul_f32 v[34:35], v[34:35], v[222:223]
	v_pk_fma_f32 v[222:223], v[42:43], v[222:223], v[188:189] neg_lo:[0,0,1] neg_hi:[0,0,1]
	v_pk_fma_f32 v[162:163], v[42:43], v[162:163], v[34:35]
	v_pk_mul_f32 v[188:189], v[36:37], v[164:165]
	v_pk_mul_f32 v[36:37], v[36:37], v[224:225]
	v_pk_fma_f32 v[224:225], v[44:45], v[224:225], v[188:189] neg_lo:[0,0,1] neg_hi:[0,0,1]
	v_pk_fma_f32 v[164:165], v[44:45], v[164:165], v[36:37]
	v_cvt_pk_bf16_f32 v46, v218, v219
	v_cvt_pk_bf16_f32 v47, v220, v221
	v_cvt_pk_bf16_f32 v48, v222, v223
	v_cvt_pk_bf16_f32 v49, v224, v225
	v_cvt_pk_bf16_f32 v42, v226, v227
	v_cvt_pk_bf16_f32 v43, v228, v229
	v_cvt_pk_bf16_f32 v44, v162, v163
	v_cvt_pk_bf16_f32 v45, v164, v165
	s_add_u32 s62, s60, 0x48000
	s_addc_u32 s63, s61, 0
	s_nop 0
	global_store_dwordx4 v192, v[46:49], s[62:63]
	global_store_dwordx4 v192, v[42:45], s[62:63] offset:64
	v_mul_f32_e32 v30, v30, v253
	v_mul_f32_e32 v31, v31, v253
	v_mul_f32_e32 v32, v32, v253
	v_mul_f32_e32 v33, v33, v253
	v_mul_f32_e32 v26, v26, v253
	v_mul_f32_e32 v27, v27, v253
	v_mul_f32_e32 v28, v28, v253
	v_mul_f32_e32 v29, v29, v253
	v_mul_f32_e32 v22, v22, v253
	v_mul_f32_e32 v23, v23, v253
	v_mul_f32_e32 v24, v24, v253
	v_mul_f32_e32 v25, v25, v253
	v_mul_f32_e32 v18, v18, v253
	v_mul_f32_e32 v19, v19, v253
	v_mul_f32_e32 v20, v20, v253
	v_mul_f32_e32 v21, v21, v253
	v_pk_mul_f32 v[30:31], v[30:31], v[130:131]
	v_pk_mul_f32 v[22:23], v[22:23], v[138:139]
	v_pk_mul_f32 v[32:33], v[32:33], v[132:133]
	v_pk_mul_f32 v[24:25], v[24:25], v[140:141]
	v_pk_mul_f32 v[26:27], v[26:27], v[134:135]
	v_pk_mul_f32 v[18:19], v[18:19], v[142:143]
	v_pk_mul_f32 v[28:29], v[28:29], v[136:137]
	v_pk_mul_f32 v[20:21], v[20:21], v[144:145]
	s_waitcnt vmcnt(10)
	v_pk_mul_f32 v[188:189], v[22:23], v[154:155]
	v_pk_mul_f32 v[22:23], v[22:23], v[146:147]
	v_pk_fma_f32 v[146:147], v[30:31], v[146:147], v[188:189] neg_lo:[0,0,1] neg_hi:[0,0,1]
	v_pk_fma_f32 v[154:155], v[30:31], v[154:155], v[22:23]
	v_pk_mul_f32 v[188:189], v[24:25], v[156:157]
	v_pk_mul_f32 v[24:25], v[24:25], v[148:149]
	v_pk_fma_f32 v[148:149], v[32:33], v[148:149], v[188:189] neg_lo:[0,0,1] neg_hi:[0,0,1]
	v_pk_fma_f32 v[156:157], v[32:33], v[156:157], v[24:25]
	v_pk_mul_f32 v[188:189], v[18:19], v[158:159]
	v_pk_mul_f32 v[18:19], v[18:19], v[150:151]
	v_pk_fma_f32 v[150:151], v[26:27], v[150:151], v[188:189] neg_lo:[0,0,1] neg_hi:[0,0,1]
	v_pk_fma_f32 v[158:159], v[26:27], v[158:159], v[18:19]
	v_pk_mul_f32 v[188:189], v[20:21], v[160:161]
	v_pk_mul_f32 v[20:21], v[20:21], v[152:153]
	v_pk_fma_f32 v[152:153], v[28:29], v[152:153], v[188:189] neg_lo:[0,0,1] neg_hi:[0,0,1]
	v_pk_fma_f32 v[160:161], v[28:29], v[160:161], v[20:21]
	v_cvt_pk_bf16_f32 v30, v146, v147
	v_cvt_pk_bf16_f32 v31, v148, v149
	v_cvt_pk_bf16_f32 v32, v150, v151
	v_cvt_pk_bf16_f32 v33, v152, v153
	v_cvt_pk_bf16_f32 v26, v154, v155
	v_cvt_pk_bf16_f32 v27, v156, v157
	v_cvt_pk_bf16_f32 v28, v158, v159
	v_cvt_pk_bf16_f32 v29, v160, v161
	s_add_u32 s62, s60, 0x50000
	s_addc_u32 s63, s61, 0
	s_nop 0
	global_store_dwordx4 v192, v[30:33], s[62:63]
	global_store_dwordx4 v192, v[26:29], s[62:63] offset:64
	v_mul_f32_e32 v14, v14, v254
	v_mul_f32_e32 v15, v15, v254
	v_mul_f32_e32 v16, v16, v254
	v_mul_f32_e32 v17, v17, v254
	v_mul_f32_e32 v10, v10, v254
	v_mul_f32_e32 v11, v11, v254
	v_mul_f32_e32 v12, v12, v254
	v_mul_f32_e32 v13, v13, v254
	v_mul_f32_e32 v6, v6, v254
	v_mul_f32_e32 v7, v7, v254
	v_mul_f32_e32 v8, v8, v254
	v_mul_f32_e32 v9, v9, v254
	v_mul_f32_e32 v2, v2, v254
	v_mul_f32_e32 v3, v3, v254
	v_mul_f32_e32 v4, v4, v254
	v_mul_f32_e32 v5, v5, v254
	v_pk_mul_f32 v[14:15], v[14:15], v[130:131]
	v_pk_mul_f32 v[6:7], v[6:7], v[138:139]
	v_pk_mul_f32 v[16:17], v[16:17], v[132:133]
	v_pk_mul_f32 v[8:9], v[8:9], v[140:141]
	v_pk_mul_f32 v[10:11], v[10:11], v[134:135]
	v_pk_mul_f32 v[2:3], v[2:3], v[142:143]
	v_pk_mul_f32 v[12:13], v[12:13], v[136:137]
	v_pk_mul_f32 v[4:5], v[4:5], v[144:145]
	s_waitcnt vmcnt(6)
	v_pk_mul_f32 v[188:189], v[6:7], v[210:211]
	v_pk_mul_f32 v[6:7], v[6:7], v[202:203]
	v_pk_fma_f32 v[202:203], v[14:15], v[202:203], v[188:189] neg_lo:[0,0,1] neg_hi:[0,0,1]
	v_pk_fma_f32 v[210:211], v[14:15], v[210:211], v[6:7]
	v_pk_mul_f32 v[188:189], v[8:9], v[212:213]
	v_pk_mul_f32 v[8:9], v[8:9], v[204:205]
	v_pk_fma_f32 v[204:205], v[16:17], v[204:205], v[188:189] neg_lo:[0,0,1] neg_hi:[0,0,1]
	v_pk_fma_f32 v[212:213], v[16:17], v[212:213], v[8:9]
	v_pk_mul_f32 v[188:189], v[2:3], v[214:215]
	v_pk_mul_f32 v[2:3], v[2:3], v[206:207]
	v_pk_fma_f32 v[206:207], v[10:11], v[206:207], v[188:189] neg_lo:[0,0,1] neg_hi:[0,0,1]
	v_pk_fma_f32 v[214:215], v[10:11], v[214:215], v[2:3]
	v_pk_mul_f32 v[188:189], v[4:5], v[216:217]
	v_pk_mul_f32 v[4:5], v[4:5], v[208:209]
	v_pk_fma_f32 v[208:209], v[12:13], v[208:209], v[188:189] neg_lo:[0,0,1] neg_hi:[0,0,1]
	v_pk_fma_f32 v[216:217], v[12:13], v[216:217], v[4:5]
	v_cvt_pk_bf16_f32 v14, v202, v203
	v_cvt_pk_bf16_f32 v15, v204, v205
	v_cvt_pk_bf16_f32 v16, v206, v207
	v_cvt_pk_bf16_f32 v17, v208, v209
	v_cvt_pk_bf16_f32 v10, v210, v211
	v_cvt_pk_bf16_f32 v11, v212, v213
	v_cvt_pk_bf16_f32 v12, v214, v215
	v_cvt_pk_bf16_f32 v13, v216, v217
	s_add_u32 s62, s60, 0x58000
	s_addc_u32 s63, s61, 0
	s_nop 0
	global_store_dwordx4 v192, v[14:17], s[62:63]
	global_store_dwordx4 v192, v[10:13], s[62:63] offset:64
	s_branch .LBB0_635
.Lk_epi:
	v_lshrrev_b32_e32 v190, 6, v0
	v_and_b32_e32 v192, 15, v0
	v_readfirstlane_b32 s98, v190
	v_bfe_u32 v190, v0, 4, 2
	s_lshl_b32 s100, s24, 8
	s_and_b32 s99, s98, 3
	s_lshr_b32 s98, s98, 2
	s_lshl_b32 s101, s98, 6
	s_add_i32 s100, s100, s101
	v_add_u32_e32 v188, s100, v192
	v_lshlrev_b32_e32 v189, 7, v188
	v_lshl_add_u32 v189, v190, 4, v189
	s_add_u32 s58, s6, 0x10900000
	s_addc_u32 s59, s7, 0
	s_nop 0
	global_load_dwordx4 v[202:205], v189, s[58:59]
	global_load_dwordx4 v[206:209], v189, s[58:59] offset:2048
	s_add_u32 s62, s58, 0x1000
	s_addc_u32 s63, s59, 0
	s_nop 0
	global_load_dwordx4 v[210:213], v189, s[62:63]
	s_add_u32 s62, s58, 0x1800
	s_addc_u32 s63, s59, 0
	s_nop 0
	global_load_dwordx4 v[214:217], v189, s[62:63]
	s_add_u32 s62, s58, 0x4000
	s_addc_u32 s63, s59, 0
	s_nop 0
	global_load_dwordx4 v[218:221], v189, s[62:63]
	s_add_u32 s62, s58, 0x4800
	s_addc_u32 s63, s59, 0
	s_nop 0
	global_load_dwordx4 v[222:225], v189, s[62:63]
	s_add_u32 s62, s58, 0x5000
	s_addc_u32 s63, s59, 0
	s_nop 0
	global_load_dwordx4 v[226:229], v189, s[62:63]
	s_add_u32 s62, s58, 0x5800
	s_addc_u32 s63, s59, 0
	s_nop 0
	global_load_dwordx4 v[162:165], v189, s[62:63]
	v_and_b32_e32 v191, 0xfff, v188
	v_lshlrev_b32_e32 v191, 8, v191
	v_lshl_add_u32 v191, v190, 5, v191
	s_lshl_b32 s100, s99, 7
	v_lshlrev_b32_e32 v192, 9, v188
	v_add_u32_e32 v192, s100, v192
	s_add_u32 s60, s6, 0x7900000
	s_addc_u32 s61, s7, 0
	v_lshl_add_u32 v192, v190, 4, v192
	v_mov_b32_e32 v193, 0x200a8
	ds_read_b64 v[188:189], v193
	v_lshlrev_b32_e32 v194, 5, v190
	s_waitcnt lgkmcnt(0)
	v_readfirstlane_b32 s62, v188
	v_readfirstlane_b32 s63, v189
	s_nop 3
	s_nop 0
	global_load_dwordx4 v[130:133], v194, s[62:63]
	global_load_dwordx4 v[134:137], v194, s[62:63] offset:16
	global_load_dwordx4 v[138:141], v194, s[62:63] offset:128
	global_load_dwordx4 v[142:145], v194, s[62:63] offset:144
	v_mov_b32_e32 v193, 0x200e0
	ds_read_b64 v[188:189], v193
	s_and_b32 s64, s24, 15
	s_lshr_b32 s65, s24, 4
	s_lshl_b32 s65, s65, 7
	s_lshl_b32 s100, s98, 6
	s_add_i32 s65, s65, s100
	s_lshl_b32 s65, s65, 10
	s_lshl_b32 s100, s99, 8
	s_add_i32 s65, s65, s100
	s_add_i32 s65, s65, 0x40c0000
	s_waitcnt lgkmcnt(0)
	v_readfirstlane_b32 s96, v188
	v_readfirstlane_b32 s97, v189
	s_nop 3
	s_add_u32 s96, s96, s65
	s_addc_u32 s97, s97, 0
	s_add_u32 s58, s6, 0x5310000
	s_addc_u32 s59, s7, 0
	s_nop 0
	global_load_dwordx4 v[146:149], v191, s[58:59]
	global_load_dwordx4 v[150:153], v191, s[58:59] offset:16
	global_load_dwordx4 v[154:157], v191, s[58:59] offset:128
	global_load_dwordx4 v[158:161], v191, s[58:59] offset:144
	v_and_b32_e32 v193, 63, v0
	v_xor_b32_e32 v194, 32, v193
	v_xor_b32_e32 v193, 16, v193
	v_lshlrev_b32_e32 v193, 2, v193
	v_lshlrev_b32_e32 v194, 2, v194
	v_mov_b32_e32 v188, 0x3a800000
	s_waitcnt vmcnt(8)
	v_add_f32_e32 v202, v202, v203
	v_add_f32_e32 v204, v204, v205
	v_add_f32_e32 v202, v202, v204
	v_add_f32_e32 v206, v206, v207
	v_add_f32_e32 v208, v208, v209
	v_add_f32_e32 v206, v206, v208
	v_add_f32_e32 v210, v210, v211
	v_add_f32_e32 v212, v212, v213
	v_add_f32_e32 v210, v210, v212
	v_add_f32_e32 v214, v214, v215
	v_add_f32_e32 v216, v216, v217
	v_add_f32_e32 v214, v214, v216
	v_add_f32_e32 v218, v218, v219
	v_add_f32_e32 v220, v220, v221
	v_add_f32_e32 v218, v218, v220
	v_add_f32_e32 v222, v222, v223
	v_add_f32_e32 v224, v224, v225
	v_add_f32_e32 v222, v222, v224
	v_add_f32_e32 v226, v226, v227
	v_add_f32_e32 v228, v228, v229
	v_add_f32_e32 v226, v226, v228
	v_add_f32_e32 v162, v162, v163
	v_add_f32_e32 v164, v164, v165
	v_add_f32_e32 v162, v162, v164
	ds_bpermute_b32 v203, v193, v202
	ds_bpermute_b32 v207, v193, v206
	ds_bpermute_b32 v211, v193, v210
	ds_bpermute_b32 v215, v193, v214
	ds_bpermute_b32 v219, v193, v218
	ds_bpermute_b32 v223, v193, v222
	ds_bpermute_b32 v227, v193, v226
	ds_bpermute_b32 v163, v193, v162
	s_waitcnt lgkmcnt(7)
	v_add_f32_e32 v202, v202, v203
	s_waitcnt lgkmcnt(6)
	v_add_f32_e32 v206, v206, v207
	s_waitcnt lgkmcnt(5)
	v_add_f32_e32 v210, v210, v211
	s_waitcnt lgkmcnt(4)
	v_add_f32_e32 v214, v214, v215
	s_waitcnt lgkmcnt(3)
	v_add_f32_e32 v218, v218, v219
	s_waitcnt lgkmcnt(2)
	v_add_f32_e32 v222, v222, v223
	s_waitcnt lgkmcnt(1)
	v_add_f32_e32 v226, v226, v227
	s_waitcnt lgkmcnt(0)
	v_add_f32_e32 v162, v162, v163
	ds_bpermute_b32 v203, v194, v202
	ds_bpermute_b32 v207, v194, v206
	ds_bpermute_b32 v211, v194, v210
	ds_bpermute_b32 v215, v194, v214
	ds_bpermute_b32 v219, v194, v218
	ds_bpermute_b32 v223, v194, v222
	ds_bpermute_b32 v227, v194, v226
	ds_bpermute_b32 v163, v194, v162
	s_waitcnt lgkmcnt(7)
	v_add_f32_e32 v202, v202, v203
	s_waitcnt lgkmcnt(6)
	v_add_f32_e32 v206, v206, v207
	s_waitcnt lgkmcnt(5)
	v_add_f32_e32 v210, v210, v211
	s_waitcnt lgkmcnt(4)
	v_add_f32_e32 v214, v214, v215
	s_waitcnt lgkmcnt(3)
	v_add_f32_e32 v218, v218, v219
	s_waitcnt lgkmcnt(2)
	v_add_f32_e32 v222, v222, v223
	s_waitcnt lgkmcnt(1)
	v_add_f32_e32 v226, v226, v227
	s_waitcnt lgkmcnt(0)
	v_add_f32_e32 v162, v162, v163
	v_fmaak_f32 v202, v188, v202, 0x358637bd
	v_rsq_f32_e32 v230, v202
	v_fmaak_f32 v206, v188, v206, 0x358637bd
	v_rsq_f32_e32 v248, v206
	v_fmaak_f32 v210, v188, v210, 0x358637bd
	v_rsq_f32_e32 v249, v210
	v_fmaak_f32 v214, v188, v214, 0x358637bd
	v_rsq_f32_e32 v250, v214
	v_fmaak_f32 v218, v188, v218, 0x358637bd
	v_rsq_f32_e32 v251, v218
	v_fmaak_f32 v222, v188, v222, 0x358637bd
	v_rsq_f32_e32 v252, v222
	v_fmaak_f32 v226, v188, v226, 0x358637bd
	v_rsq_f32_e32 v253, v226
	v_fmaak_f32 v162, v188, v162, 0x358637bd
	v_rsq_f32_e32 v254, v162
	s_nop 0
	s_add_u32 s62, s58, 0x1000
	s_addc_u32 s63, s59, 0
	s_nop 0
	global_load_dwordx4 v[202:205], v191, s[62:63]
	global_load_dwordx4 v[206:209], v191, s[62:63] offset:16
	global_load_dwordx4 v[210:213], v191, s[62:63] offset:128
	global_load_dwordx4 v[214:217], v191, s[62:63] offset:144
	v_mul_f32_e32 v126, v126, v230
	v_mul_f32_e32 v127, v127, v230
	v_mul_f32_e32 v128, v128, v230
	v_mul_f32_e32 v129, v129, v230
	v_mul_f32_e32 v122, v122, v230
	v_mul_f32_e32 v123, v123, v230
	v_mul_f32_e32 v124, v124, v230
	v_mul_f32_e32 v125, v125, v230
	v_mul_f32_e32 v118, v118, v230
	v_mul_f32_e32 v119, v119, v230
	v_mul_f32_e32 v120, v120, v230
	v_mul_f32_e32 v121, v121, v230
	v_mul_f32_e32 v114, v114, v230
	v_mul_f32_e32 v115, v115, v230
	v_mul_f32_e32 v116, v116, v230
	v_mul_f32_e32 v117, v117, v230
	v_mul_f32_e32 v188, v126, v126
	v_mul_f32_e32 v189, v128, v128
	v_fmac_f32_e32 v188, v127, v127
	v_fmac_f32_e32 v189, v129, v129
	v_add_f32_e32 v230, v188, v189
	v_mul_f32_e32 v188, v122, v122
	v_mul_f32_e32 v189, v124, v124
	v_fmac_f32_e32 v188, v123, v123
	v_fmac_f32_e32 v189, v125, v125
	v_add_f32_e32 v188, v188, v189
	v_add_f32_e32 v230, v230, v188
	v_mul_f32_e32 v188, v118, v118
	v_mul_f32_e32 v189, v120, v120
	v_fmac_f32_e32 v188, v119, v119
	v_fmac_f32_e32 v189, v121, v121
	v_add_f32_e32 v188, v188, v189
	v_add_f32_e32 v230, v230, v188
	v_mul_f32_e32 v188, v114, v114
	v_mul_f32_e32 v189, v116, v116
	v_fmac_f32_e32 v188, v115, v115
	v_fmac_f32_e32 v189, v117, v117
	v_add_f32_e32 v188, v188, v189
	v_add_f32_e32 v230, v230, v188
	v_mul_f32_e32 v110, v110, v248
	v_mul_f32_e32 v111, v111, v248
	v_mul_f32_e32 v112, v112, v248
	v_mul_f32_e32 v113, v113, v248
	v_mul_f32_e32 v106, v106, v248
	v_mul_f32_e32 v107, v107, v248
	v_mul_f32_e32 v108, v108, v248
	v_mul_f32_e32 v109, v109, v248
	v_mul_f32_e32 v102, v102, v248
	v_mul_f32_e32 v103, v103, v248
	v_mul_f32_e32 v104, v104, v248
	v_mul_f32_e32 v105, v105, v248
	v_mul_f32_e32 v98, v98, v248
	v_mul_f32_e32 v99, v99, v248
	v_mul_f32_e32 v100, v100, v248
	v_mul_f32_e32 v101, v101, v248
	v_mul_f32_e32 v188, v110, v110
	v_mul_f32_e32 v189, v112, v112
	v_fmac_f32_e32 v188, v111, v111
	v_fmac_f32_e32 v189, v113, v113
	v_add_f32_e32 v248, v188, v189
	v_mul_f32_e32 v188, v106, v106
	v_mul_f32_e32 v189, v108, v108
	v_fmac_f32_e32 v188, v107, v107
	v_fmac_f32_e32 v189, v109, v109
	v_add_f32_e32 v188, v188, v189
	v_add_f32_e32 v248, v248, v188
	v_mul_f32_e32 v188, v102, v102
	v_mul_f32_e32 v189, v104, v104
	v_fmac_f32_e32 v188, v103, v103
	v_fmac_f32_e32 v189, v105, v105
	v_add_f32_e32 v188, v188, v189
	v_add_f32_e32 v248, v248, v188
	v_mul_f32_e32 v188, v98, v98
	v_mul_f32_e32 v189, v100, v100
	v_fmac_f32_e32 v188, v99, v99
	v_fmac_f32_e32 v189, v101, v101
	v_add_f32_e32 v188, v188, v189
	v_add_f32_e32 v248, v248, v188
	v_mul_f32_e32 v94, v94, v249
	v_mul_f32_e32 v95, v95, v249
	v_mul_f32_e32 v96, v96, v249
	v_mul_f32_e32 v97, v97, v249
	v_mul_f32_e32 v90, v90, v249
	v_mul_f32_e32 v91, v91, v249
	v_mul_f32_e32 v92, v92, v249
	v_mul_f32_e32 v93, v93, v249
	v_mul_f32_e32 v86, v86, v249
	v_mul_f32_e32 v87, v87, v249
	v_mul_f32_e32 v88, v88, v249
	v_mul_f32_e32 v89, v89, v249
	v_mul_f32_e32 v82, v82, v249
	v_mul_f32_e32 v83, v83, v249
	v_mul_f32_e32 v84, v84, v249
	v_mul_f32_e32 v85, v85, v249
	v_mul_f32_e32 v188, v94, v94
	v_mul_f32_e32 v189, v96, v96
	v_fmac_f32_e32 v188, v95, v95
	v_fmac_f32_e32 v189, v97, v97
	v_add_f32_e32 v249, v188, v189
	v_mul_f32_e32 v188, v90, v90
	v_mul_f32_e32 v189, v92, v92
	v_fmac_f32_e32 v188, v91, v91
	v_fmac_f32_e32 v189, v93, v93
	v_add_f32_e32 v188, v188, v189
	v_add_f32_e32 v249, v249, v188
	v_mul_f32_e32 v188, v86, v86
	v_mul_f32_e32 v189, v88, v88
	v_fmac_f32_e32 v188, v87, v87
	v_fmac_f32_e32 v189, v89, v89
	v_add_f32_e32 v188, v188, v189
	v_add_f32_e32 v249, v249, v188
	v_mul_f32_e32 v188, v82, v82
	v_mul_f32_e32 v189, v84, v84
	v_fmac_f32_e32 v188, v83, v83
	v_fmac_f32_e32 v189, v85, v85
	v_add_f32_e32 v188, v188, v189
	v_add_f32_e32 v249, v249, v188
	v_mul_f32_e32 v78, v78, v250
	v_mul_f32_e32 v79, v79, v250
	v_mul_f32_e32 v80, v80, v250
	v_mul_f32_e32 v81, v81, v250
	v_mul_f32_e32 v74, v74, v250
	v_mul_f32_e32 v75, v75, v250
	v_mul_f32_e32 v76, v76, v250
	v_mul_f32_e32 v77, v77, v250
	v_mul_f32_e32 v70, v70, v250
	v_mul_f32_e32 v71, v71, v250
	v_mul_f32_e32 v72, v72, v250
	v_mul_f32_e32 v73, v73, v250
	v_mul_f32_e32 v66, v66, v250
	v_mul_f32_e32 v67, v67, v250
	v_mul_f32_e32 v68, v68, v250
	v_mul_f32_e32 v69, v69, v250
	v_mul_f32_e32 v188, v78, v78
	v_mul_f32_e32 v189, v80, v80
	v_fmac_f32_e32 v188, v79, v79
	v_fmac_f32_e32 v189, v81, v81
	v_add_f32_e32 v250, v188, v189
	v_mul_f32_e32 v188, v74, v74
	v_mul_f32_e32 v189, v76, v76
	v_fmac_f32_e32 v188, v75, v75
	v_fmac_f32_e32 v189, v77, v77
	v_add_f32_e32 v188, v188, v189
	v_add_f32_e32 v250, v250, v188
	v_mul_f32_e32 v188, v70, v70
	v_mul_f32_e32 v189, v72, v72
	v_fmac_f32_e32 v188, v71, v71
	v_fmac_f32_e32 v189, v73, v73
	v_add_f32_e32 v188, v188, v189
	v_add_f32_e32 v250, v250, v188
	v_mul_f32_e32 v188, v66, v66
	v_mul_f32_e32 v189, v68, v68
	v_fmac_f32_e32 v188, v67, v67
	v_fmac_f32_e32 v189, v69, v69
	v_add_f32_e32 v188, v188, v189
	v_add_f32_e32 v250, v250, v188
	v_mul_f32_e32 v62, v62, v251
	v_mul_f32_e32 v63, v63, v251
	v_mul_f32_e32 v64, v64, v251
	v_mul_f32_e32 v65, v65, v251
	v_mul_f32_e32 v58, v58, v251
	v_mul_f32_e32 v59, v59, v251
	v_mul_f32_e32 v60, v60, v251
	v_mul_f32_e32 v61, v61, v251
	v_mul_f32_e32 v54, v54, v251
	v_mul_f32_e32 v55, v55, v251
	v_mul_f32_e32 v56, v56, v251
	v_mul_f32_e32 v57, v57, v251
	v_mul_f32_e32 v50, v50, v251
	v_mul_f32_e32 v51, v51, v251
	v_mul_f32_e32 v52, v52, v251
	v_mul_f32_e32 v53, v53, v251
	v_mul_f32_e32 v188, v62, v62
	v_mul_f32_e32 v189, v64, v64
	v_fmac_f32_e32 v188, v63, v63
	v_fmac_f32_e32 v189, v65, v65
	v_add_f32_e32 v251, v188, v189
	v_mul_f32_e32 v188, v58, v58
	v_mul_f32_e32 v189, v60, v60
	v_fmac_f32_e32 v188, v59, v59
	v_fmac_f32_e32 v189, v61, v61
	v_add_f32_e32 v188, v188, v189
	v_add_f32_e32 v251, v251, v188
	v_mul_f32_e32 v188, v54, v54
	v_mul_f32_e32 v189, v56, v56
	v_fmac_f32_e32 v188, v55, v55
	v_fmac_f32_e32 v189, v57, v57
	v_add_f32_e32 v188, v188, v189
	v_add_f32_e32 v251, v251, v188
	v_mul_f32_e32 v188, v50, v50
	v_mul_f32_e32 v189, v52, v52
	v_fmac_f32_e32 v188, v51, v51
	v_fmac_f32_e32 v189, v53, v53
	v_add_f32_e32 v188, v188, v189
	v_add_f32_e32 v251, v251, v188
	v_mul_f32_e32 v46, v46, v252
	v_mul_f32_e32 v47, v47, v252
	v_mul_f32_e32 v48, v48, v252
	v_mul_f32_e32 v49, v49, v252
	v_mul_f32_e32 v42, v42, v252
	v_mul_f32_e32 v43, v43, v252
	v_mul_f32_e32 v44, v44, v252
	v_mul_f32_e32 v45, v45, v252
	v_mul_f32_e32 v38, v38, v252
	v_mul_f32_e32 v39, v39, v252
	v_mul_f32_e32 v40, v40, v252
	v_mul_f32_e32 v41, v41, v252
	v_mul_f32_e32 v34, v34, v252
	v_mul_f32_e32 v35, v35, v252
	v_mul_f32_e32 v36, v36, v252
	v_mul_f32_e32 v37, v37, v252
	v_mul_f32_e32 v188, v46, v46
	v_mul_f32_e32 v189, v48, v48
	v_fmac_f32_e32 v188, v47, v47
	v_fmac_f32_e32 v189, v49, v49
	v_add_f32_e32 v252, v188, v189
	v_mul_f32_e32 v188, v42, v42
	v_mul_f32_e32 v189, v44, v44
	v_fmac_f32_e32 v188, v43, v43
	v_fmac_f32_e32 v189, v45, v45
	v_add_f32_e32 v188, v188, v189
	v_add_f32_e32 v252, v252, v188
	v_mul_f32_e32 v188, v38, v38
	v_mul_f32_e32 v189, v40, v40
	v_fmac_f32_e32 v188, v39, v39
	v_fmac_f32_e32 v189, v41, v41
	v_add_f32_e32 v188, v188, v189
	v_add_f32_e32 v252, v252, v188
	v_mul_f32_e32 v188, v34, v34
	v_mul_f32_e32 v189, v36, v36
	v_fmac_f32_e32 v188, v35, v35
	v_fmac_f32_e32 v189, v37, v37
	v_add_f32_e32 v188, v188, v189
	v_add_f32_e32 v252, v252, v188
	v_mul_f32_e32 v30, v30, v253
	v_mul_f32_e32 v31, v31, v253
	v_mul_f32_e32 v32, v32, v253
	v_mul_f32_e32 v33, v33, v253
	v_mul_f32_e32 v26, v26, v253
	v_mul_f32_e32 v27, v27, v253
	v_mul_f32_e32 v28, v28, v253
	v_mul_f32_e32 v29, v29, v253
	v_mul_f32_e32 v22, v22, v253
	v_mul_f32_e32 v23, v23, v253
	v_mul_f32_e32 v24, v24, v253
	v_mul_f32_e32 v25, v25, v253
	v_mul_f32_e32 v18, v18, v253
	v_mul_f32_e32 v19, v19, v253
	v_mul_f32_e32 v20, v20, v253
	v_mul_f32_e32 v21, v21, v253
	v_mul_f32_e32 v188, v30, v30
	v_mul_f32_e32 v189, v32, v32
	v_fmac_f32_e32 v188, v31, v31
	v_fmac_f32_e32 v189, v33, v33
	v_add_f32_e32 v253, v188, v189
	v_mul_f32_e32 v188, v26, v26
	v_mul_f32_e32 v189, v28, v28
	v_fmac_f32_e32 v188, v27, v27
	v_fmac_f32_e32 v189, v29, v29
	v_add_f32_e32 v188, v188, v189
	v_add_f32_e32 v253, v253, v188
	v_mul_f32_e32 v188, v22, v22
	v_mul_f32_e32 v189, v24, v24
	v_fmac_f32_e32 v188, v23, v23
	v_fmac_f32_e32 v189, v25, v25
	v_add_f32_e32 v188, v188, v189
	v_add_f32_e32 v253, v253, v188
	v_mul_f32_e32 v188, v18, v18
	v_mul_f32_e32 v189, v20, v20
	v_fmac_f32_e32 v188, v19, v19
	v_fmac_f32_e32 v189, v21, v21
	v_add_f32_e32 v188, v188, v189
	v_add_f32_e32 v253, v253, v188
	v_mul_f32_e32 v14, v14, v254
	v_mul_f32_e32 v15, v15, v254
	v_mul_f32_e32 v16, v16, v254
	v_mul_f32_e32 v17, v17, v254
	v_mul_f32_e32 v10, v10, v254
	v_mul_f32_e32 v11, v11, v254
	v_mul_f32_e32 v12, v12, v254
	v_mul_f32_e32 v13, v13, v254
	v_mul_f32_e32 v6, v6, v254
	v_mul_f32_e32 v7, v7, v254
	v_mul_f32_e32 v8, v8, v254
	v_mul_f32_e32 v9, v9, v254
	v_mul_f32_e32 v2, v2, v254
	v_mul_f32_e32 v3, v3, v254
	v_mul_f32_e32 v4, v4, v254
	v_mul_f32_e32 v5, v5, v254
	v_mul_f32_e32 v188, v14, v14
	v_mul_f32_e32 v189, v16, v16
	v_fmac_f32_e32 v188, v15, v15
	v_fmac_f32_e32 v189, v17, v17
	v_add_f32_e32 v254, v188, v189
	v_mul_f32_e32 v188, v10, v10
	v_mul_f32_e32 v189, v12, v12
	v_fmac_f32_e32 v188, v11, v11
	v_fmac_f32_e32 v189, v13, v13
	v_add_f32_e32 v188, v188, v189
	v_add_f32_e32 v254, v254, v188
	v_mul_f32_e32 v188, v6, v6
	v_mul_f32_e32 v189, v8, v8
	v_fmac_f32_e32 v188, v7, v7
	v_fmac_f32_e32 v189, v9, v9
	v_add_f32_e32 v188, v188, v189
	v_add_f32_e32 v254, v254, v188
	v_mul_f32_e32 v188, v2, v2
	v_mul_f32_e32 v189, v4, v4
	v_fmac_f32_e32 v188, v3, v3
	v_fmac_f32_e32 v189, v5, v5
	v_add_f32_e32 v188, v188, v189
	v_add_f32_e32 v254, v254, v188
	ds_bpermute_b32 v218, v193, v230
	ds_bpermute_b32 v219, v193, v248
	ds_bpermute_b32 v220, v193, v249
	ds_bpermute_b32 v221, v193, v250
	ds_bpermute_b32 v222, v193, v251
	ds_bpermute_b32 v223, v193, v252
	ds_bpermute_b32 v224, v193, v253
	ds_bpermute_b32 v225, v193, v254
	s_waitcnt lgkmcnt(7)
	v_add_f32_e32 v230, v230, v218
	s_waitcnt lgkmcnt(6)
	v_add_f32_e32 v248, v248, v219
	s_waitcnt lgkmcnt(5)
	v_add_f32_e32 v249, v249, v220
	s_waitcnt lgkmcnt(4)
	v_add_f32_e32 v250, v250, v221
	s_waitcnt lgkmcnt(3)
	v_add_f32_e32 v251, v251, v222
	s_waitcnt lgkmcnt(2)
	v_add_f32_e32 v252, v252, v223
	s_waitcnt lgkmcnt(1)
	v_add_f32_e32 v253, v253, v224
	s_waitcnt lgkmcnt(0)
	v_add_f32_e32 v254, v254, v225
	ds_bpermute_b32 v218, v194, v230
	ds_bpermute_b32 v219, v194, v248
	ds_bpermute_b32 v220, v194, v249
	ds_bpermute_b32 v221, v194, v250
	ds_bpermute_b32 v222, v194, v251
	ds_bpermute_b32 v223, v194, v252
	ds_bpermute_b32 v224, v194, v253
	ds_bpermute_b32 v225, v194, v254
	s_waitcnt lgkmcnt(7)
	v_add_f32_e32 v230, v230, v218
	s_waitcnt lgkmcnt(6)
	v_add_f32_e32 v248, v248, v219
	s_waitcnt lgkmcnt(5)
	v_add_f32_e32 v249, v249, v220
	s_waitcnt lgkmcnt(4)
	v_add_f32_e32 v250, v250, v221
	s_waitcnt lgkmcnt(3)
	v_add_f32_e32 v251, v251, v222
	s_waitcnt lgkmcnt(2)
	v_add_f32_e32 v252, v252, v223
	s_waitcnt lgkmcnt(1)
	v_add_f32_e32 v253, v253, v224
	s_waitcnt lgkmcnt(0)
	v_add_f32_e32 v254, v254, v225
	v_mov_b32_e32 v188, 0x3c800000
	v_fmaak_f32 v230, v188, v230, 0x358637bd
	v_rsq_f32_e32 v230, v230
	v_fmaak_f32 v248, v188, v248, 0x358637bd
	v_rsq_f32_e32 v248, v248
	v_fmaak_f32 v249, v188, v249, 0x358637bd
	v_rsq_f32_e32 v249, v249
	v_fmaak_f32 v250, v188, v250, 0x358637bd
	v_rsq_f32_e32 v250, v250
	v_fmaak_f32 v251, v188, v251, 0x358637bd
	v_rsq_f32_e32 v251, v251
	v_fmaak_f32 v252, v188, v252, 0x358637bd
	v_rsq_f32_e32 v252, v252
	v_fmaak_f32 v253, v188, v253, 0x358637bd
	v_rsq_f32_e32 v253, v253
	v_fmaak_f32 v254, v188, v254, 0x358637bd
	v_rsq_f32_e32 v254, v254
	s_nop 0
	s_add_u32 s62, s58, 0x2000
	s_addc_u32 s63, s59, 0
	s_nop 0
	global_load_dwordx4 v[218:221], v191, s[62:63]
	global_load_dwordx4 v[222:225], v191, s[62:63] offset:16
	global_load_dwordx4 v[226:229], v191, s[62:63] offset:128
	global_load_dwordx4 v[162:165], v191, s[62:63] offset:144
	s_waitcnt vmcnt(12)
	v_mul_f32_e32 v126, v126, v230
	v_mul_f32_e32 v127, v127, v230
	v_mul_f32_e32 v128, v128, v230
	v_mul_f32_e32 v129, v129, v230
	v_mul_f32_e32 v122, v122, v230
	v_mul_f32_e32 v123, v123, v230
	v_mul_f32_e32 v124, v124, v230
	v_mul_f32_e32 v125, v125, v230
	v_mul_f32_e32 v118, v118, v230
	v_mul_f32_e32 v119, v119, v230
	v_mul_f32_e32 v120, v120, v230
	v_mul_f32_e32 v121, v121, v230
	v_mul_f32_e32 v114, v114, v230
	v_mul_f32_e32 v115, v115, v230
	v_mul_f32_e32 v116, v116, v230
	v_mul_f32_e32 v117, v117, v230
	v_pk_mul_f32 v[126:127], v[126:127], v[130:131]
	v_pk_mul_f32 v[118:119], v[118:119], v[138:139]
	v_pk_mul_f32 v[128:129], v[128:129], v[132:133]
	v_pk_mul_f32 v[120:121], v[120:121], v[140:141]
	v_pk_mul_f32 v[122:123], v[122:123], v[134:135]
	v_pk_mul_f32 v[114:115], v[114:115], v[142:143]
	v_pk_mul_f32 v[124:125], v[124:125], v[136:137]
	v_pk_mul_f32 v[116:117], v[116:117], v[144:145]
	s_waitcnt vmcnt(8)
	v_pk_mul_f32 v[188:189], v[118:119], v[154:155]
	v_pk_mul_f32 v[118:119], v[118:119], v[146:147]
	v_pk_fma_f32 v[146:147], v[126:127], v[146:147], v[188:189] neg_lo:[0,0,1] neg_hi:[0,0,1]
	v_pk_fma_f32 v[154:155], v[126:127], v[154:155], v[118:119]
	v_pk_mul_f32 v[188:189], v[120:121], v[156:157]
	v_pk_mul_f32 v[120:121], v[120:121], v[148:149]
	v_pk_fma_f32 v[148:149], v[128:129], v[148:149], v[188:189] neg_lo:[0,0,1] neg_hi:[0,0,1]
	v_pk_fma_f32 v[156:157], v[128:129], v[156:157], v[120:121]
	v_pk_mul_f32 v[188:189], v[114:115], v[158:159]
	v_pk_mul_f32 v[114:115], v[114:115], v[150:151]
	v_pk_fma_f32 v[150:151], v[122:123], v[150:151], v[188:189] neg_lo:[0,0,1] neg_hi:[0,0,1]
	v_pk_fma_f32 v[158:159], v[122:123], v[158:159], v[114:115]
	v_pk_mul_f32 v[188:189], v[116:117], v[160:161]
	v_pk_mul_f32 v[116:117], v[116:117], v[152:153]
	v_pk_fma_f32 v[152:153], v[124:125], v[152:153], v[188:189] neg_lo:[0,0,1] neg_hi:[0,0,1]
	v_pk_fma_f32 v[160:161], v[124:125], v[160:161], v[116:117]
	v_cvt_pk_bf16_f32 v126, v146, v147
	v_cvt_pk_bf16_f32 v127, v148, v149
	v_cvt_pk_bf16_f32 v128, v150, v151
	v_cvt_pk_bf16_f32 v129, v152, v153
	v_cvt_pk_bf16_f32 v122, v154, v155
	v_cvt_pk_bf16_f32 v123, v156, v157
	v_cvt_pk_bf16_f32 v124, v158, v159
	v_cvt_pk_bf16_f32 v125, v160, v161
	s_add_u32 s62, s58, 0x3000
	s_addc_u32 s63, s59, 0
	s_nop 0
	global_load_dwordx4 v[146:149], v191, s[62:63]
	global_load_dwordx4 v[150:153], v191, s[62:63] offset:16
	global_load_dwordx4 v[154:157], v191, s[62:63] offset:128
	global_load_dwordx4 v[158:161], v191, s[62:63] offset:144
	s_nop 0
	global_store_dwordx4 v192, v[126:129], s[60:61]
	global_store_dwordx4 v192, v[122:125], s[60:61] offset:64
	v_mul_f32_e32 v110, v110, v248
	v_mul_f32_e32 v111, v111, v248
	v_mul_f32_e32 v112, v112, v248
	v_mul_f32_e32 v113, v113, v248
	v_mul_f32_e32 v106, v106, v248
	v_mul_f32_e32 v107, v107, v248
	v_mul_f32_e32 v108, v108, v248
	v_mul_f32_e32 v109, v109, v248
	v_mul_f32_e32 v102, v102, v248
	v_mul_f32_e32 v103, v103, v248
	v_mul_f32_e32 v104, v104, v248
	v_mul_f32_e32 v105, v105, v248
	v_mul_f32_e32 v98, v98, v248
	v_mul_f32_e32 v99, v99, v248
	v_mul_f32_e32 v100, v100, v248
	v_mul_f32_e32 v101, v101, v248
	v_pk_mul_f32 v[110:111], v[110:111], v[130:131]
	v_pk_mul_f32 v[102:103], v[102:103], v[138:139]
	v_pk_mul_f32 v[112:113], v[112:113], v[132:133]
	v_pk_mul_f32 v[104:105], v[104:105], v[140:141]
	v_pk_mul_f32 v[106:107], v[106:107], v[134:135]
	v_pk_mul_f32 v[98:99], v[98:99], v[142:143]
	v_pk_mul_f32 v[108:109], v[108:109], v[136:137]
	v_pk_mul_f32 v[100:101], v[100:101], v[144:145]
	s_waitcnt vmcnt(10)
	v_pk_mul_f32 v[188:189], v[102:103], v[210:211]
	v_pk_mul_f32 v[102:103], v[102:103], v[202:203]
	v_pk_fma_f32 v[202:203], v[110:111], v[202:203], v[188:189] neg_lo:[0,0,1] neg_hi:[0,0,1]
	v_pk_fma_f32 v[210:211], v[110:111], v[210:211], v[102:103]
	v_pk_mul_f32 v[188:189], v[104:105], v[212:213]
	v_pk_mul_f32 v[104:105], v[104:105], v[204:205]
	v_pk_fma_f32 v[204:205], v[112:113], v[204:205], v[188:189] neg_lo:[0,0,1] neg_hi:[0,0,1]
	v_pk_fma_f32 v[212:213], v[112:113], v[212:213], v[104:105]
	v_pk_mul_f32 v[188:189], v[98:99], v[214:215]
	v_pk_mul_f32 v[98:99], v[98:99], v[206:207]
	v_pk_fma_f32 v[206:207], v[106:107], v[206:207], v[188:189] neg_lo:[0,0,1] neg_hi:[0,0,1]
	v_pk_fma_f32 v[214:215], v[106:107], v[214:215], v[98:99]
	v_pk_mul_f32 v[188:189], v[100:101], v[216:217]
	v_pk_mul_f32 v[100:101], v[100:101], v[208:209]
	v_pk_fma_f32 v[208:209], v[108:109], v[208:209], v[188:189] neg_lo:[0,0,1] neg_hi:[0,0,1]
	v_pk_fma_f32 v[216:217], v[108:109], v[216:217], v[100:101]
	v_cvt_pk_bf16_f32 v110, v202, v203
	v_cvt_pk_bf16_f32 v111, v204, v205
	v_cvt_pk_bf16_f32 v112, v206, v207
	v_cvt_pk_bf16_f32 v113, v208, v209
	v_cvt_pk_bf16_f32 v106, v210, v211
	v_cvt_pk_bf16_f32 v107, v212, v213
	v_cvt_pk_bf16_f32 v108, v214, v215
	v_cvt_pk_bf16_f32 v109, v216, v217
	s_add_u32 s62, s58, 0x8000
	s_addc_u32 s63, s59, 0
	s_nop 0
	global_load_dwordx4 v[202:205], v191, s[62:63]
	global_load_dwordx4 v[206:209], v191, s[62:63] offset:16
	global_load_dwordx4 v[210:213], v191, s[62:63] offset:128
	global_load_dwordx4 v[214:217], v191, s[62:63] offset:144
	s_add_u32 s62, s60, 0x2000
	s_addc_u32 s63, s61, 0
	s_nop 0
	global_store_dwordx4 v192, v[110:113], s[62:63]
	global_store_dwordx4 v192, v[106:109], s[62:63] offset:64
	v_mul_f32_e32 v94, v94, v249
	v_mul_f32_e32 v95, v95, v249
	v_mul_f32_e32 v96, v96, v249
	v_mul_f32_e32 v97, v97, v249
	v_mul_f32_e32 v90, v90, v249
	v_mul_f32_e32 v91, v91, v249
	v_mul_f32_e32 v92, v92, v249
	v_mul_f32_e32 v93, v93, v249
	v_mul_f32_e32 v86, v86, v249
	v_mul_f32_e32 v87, v87, v249
	v_mul_f32_e32 v88, v88, v249
	v_mul_f32_e32 v89, v89, v249
	v_mul_f32_e32 v82, v82, v249
	v_mul_f32_e32 v83, v83, v249
	v_mul_f32_e32 v84, v84, v249
	v_mul_f32_e32 v85, v85, v249
	v_pk_mul_f32 v[94:95], v[94:95], v[130:131]
	v_pk_mul_f32 v[86:87], v[86:87], v[138:139]
	v_pk_mul_f32 v[96:97], v[96:97], v[132:133]
	v_pk_mul_f32 v[88:89], v[88:89], v[140:141]
	v_pk_mul_f32 v[90:91], v[90:91], v[134:135]
	v_pk_mul_f32 v[82:83], v[82:83], v[142:143]
	v_pk_mul_f32 v[92:93], v[92:93], v[136:137]
	v_pk_mul_f32 v[84:85], v[84:85], v[144:145]
	s_waitcnt vmcnt(12)
	v_pk_mul_f32 v[188:189], v[86:87], v[226:227]
	v_pk_mul_f32 v[86:87], v[86:87], v[218:219]
	v_pk_fma_f32 v[218:219], v[94:95], v[218:219], v[188:189] neg_lo:[0,0,1] neg_hi:[0,0,1]
	v_pk_fma_f32 v[226:227], v[94:95], v[226:227], v[86:87]
	v_pk_mul_f32 v[188:189], v[88:89], v[228:229]
	v_pk_mul_f32 v[88:89], v[88:89], v[220:221]
	v_pk_fma_f32 v[220:221], v[96:97], v[220:221], v[188:189] neg_lo:[0,0,1] neg_hi:[0,0,1]
	v_pk_fma_f32 v[228:229], v[96:97], v[228:229], v[88:89]
	v_pk_mul_f32 v[188:189], v[82:83], v[162:163]
	v_pk_mul_f32 v[82:83], v[82:83], v[222:223]
	v_pk_fma_f32 v[222:223], v[90:91], v[222:223], v[188:189] neg_lo:[0,0,1] neg_hi:[0,0,1]
	v_pk_fma_f32 v[162:163], v[90:91], v[162:163], v[82:83]
	v_pk_mul_f32 v[188:189], v[84:85], v[164:165]
	v_pk_mul_f32 v[84:85], v[84:85], v[224:225]
	v_pk_fma_f32 v[224:225], v[92:93], v[224:225], v[188:189] neg_lo:[0,0,1] neg_hi:[0,0,1]
	v_pk_fma_f32 v[164:165], v[92:93], v[164:165], v[84:85]
	v_cvt_pk_bf16_f32 v94, v218, v219
	v_cvt_pk_bf16_f32 v95, v220, v221
	v_cvt_pk_bf16_f32 v96, v222, v223
	v_cvt_pk_bf16_f32 v97, v224, v225
	v_cvt_pk_bf16_f32 v90, v226, v227
	v_cvt_pk_bf16_f32 v91, v228, v229
	v_cvt_pk_bf16_f32 v92, v162, v163
	v_cvt_pk_bf16_f32 v93, v164, v165
	s_add_u32 s62, s58, 0x9000
	s_addc_u32 s63, s59, 0
	s_nop 0
	global_load_dwordx4 v[218:221], v191, s[62:63]
	global_load_dwordx4 v[222:225], v191, s[62:63] offset:16
	global_load_dwordx4 v[226:229], v191, s[62:63] offset:128
	global_load_dwordx4 v[162:165], v191, s[62:63] offset:144
	s_add_u32 s62, s60, 0x4000
	s_addc_u32 s63, s61, 0
	s_nop 0
	global_store_dwordx4 v192, v[94:97], s[62:63]
	global_store_dwordx4 v192, v[90:93], s[62:63] offset:64
	v_mul_f32_e32 v78, v78, v250
	v_mul_f32_e32 v79, v79, v250
	v_mul_f32_e32 v80, v80, v250
	v_mul_f32_e32 v81, v81, v250
	v_mul_f32_e32 v74, v74, v250
	v_mul_f32_e32 v75, v75, v250
	v_mul_f32_e32 v76, v76, v250
	v_mul_f32_e32 v77, v77, v250
	v_mul_f32_e32 v70, v70, v250
	v_mul_f32_e32 v71, v71, v250
	v_mul_f32_e32 v72, v72, v250
	v_mul_f32_e32 v73, v73, v250
	v_mul_f32_e32 v66, v66, v250
	v_mul_f32_e32 v67, v67, v250
	v_mul_f32_e32 v68, v68, v250
	v_mul_f32_e32 v69, v69, v250
	v_pk_mul_f32 v[78:79], v[78:79], v[130:131]
	v_pk_mul_f32 v[70:71], v[70:71], v[138:139]
	v_pk_mul_f32 v[80:81], v[80:81], v[132:133]
	v_pk_mul_f32 v[72:73], v[72:73], v[140:141]
	v_pk_mul_f32 v[74:75], v[74:75], v[134:135]
	v_pk_mul_f32 v[66:67], v[66:67], v[142:143]
	v_pk_mul_f32 v[76:77], v[76:77], v[136:137]
	v_pk_mul_f32 v[68:69], v[68:69], v[144:145]
	s_waitcnt vmcnt(14)
	v_pk_mul_f32 v[188:189], v[70:71], v[154:155]
	v_pk_mul_f32 v[70:71], v[70:71], v[146:147]
	v_pk_fma_f32 v[146:147], v[78:79], v[146:147], v[188:189] neg_lo:[0,0,1] neg_hi:[0,0,1]
	v_pk_fma_f32 v[154:155], v[78:79], v[154:155], v[70:71]
	v_pk_mul_f32 v[188:189], v[72:73], v[156:157]
	v_pk_mul_f32 v[72:73], v[72:73], v[148:149]
	v_pk_fma_f32 v[148:149], v[80:81], v[148:149], v[188:189] neg_lo:[0,0,1] neg_hi:[0,0,1]
	v_pk_fma_f32 v[156:157], v[80:81], v[156:157], v[72:73]
	v_pk_mul_f32 v[188:189], v[66:67], v[158:159]
	v_pk_mul_f32 v[66:67], v[66:67], v[150:151]
	v_pk_fma_f32 v[150:151], v[74:75], v[150:151], v[188:189] neg_lo:[0,0,1] neg_hi:[0,0,1]
	v_pk_fma_f32 v[158:159], v[74:75], v[158:159], v[66:67]
	v_pk_mul_f32 v[188:189], v[68:69], v[160:161]
	v_pk_mul_f32 v[68:69], v[68:69], v[152:153]
	v_pk_fma_f32 v[152:153], v[76:77], v[152:153], v[188:189] neg_lo:[0,0,1] neg_hi:[0,0,1]
	v_pk_fma_f32 v[160:161], v[76:77], v[160:161], v[68:69]
	v_cvt_pk_bf16_f32 v78, v146, v147
	v_cvt_pk_bf16_f32 v79, v148, v149
	v_cvt_pk_bf16_f32 v80, v150, v151
	v_cvt_pk_bf16_f32 v81, v152, v153
	v_cvt_pk_bf16_f32 v74, v154, v155
	v_cvt_pk_bf16_f32 v75, v156, v157
	v_cvt_pk_bf16_f32 v76, v158, v159
	v_cvt_pk_bf16_f32 v77, v160, v161
	s_add_u32 s62, s58, 0xa000
	s_addc_u32 s63, s59, 0
	s_nop 0
	global_load_dwordx4 v[146:149], v191, s[62:63]
	global_load_dwordx4 v[150:153], v191, s[62:63] offset:16
	global_load_dwordx4 v[154:157], v191, s[62:63] offset:128
	global_load_dwordx4 v[158:161], v191, s[62:63] offset:144
	s_add_u32 s62, s60, 0x6000
	s_addc_u32 s63, s61, 0
	s_nop 0
	global_store_dwordx4 v192, v[78:81], s[62:63]
	global_store_dwordx4 v192, v[74:77], s[62:63] offset:64
	v_mul_f32_e32 v62, v62, v251
	v_mul_f32_e32 v63, v63, v251
	v_mul_f32_e32 v64, v64, v251
	v_mul_f32_e32 v65, v65, v251
	v_mul_f32_e32 v58, v58, v251
	v_mul_f32_e32 v59, v59, v251
	v_mul_f32_e32 v60, v60, v251
	v_mul_f32_e32 v61, v61, v251
	v_mul_f32_e32 v54, v54, v251
	v_mul_f32_e32 v55, v55, v251
	v_mul_f32_e32 v56, v56, v251
	v_mul_f32_e32 v57, v57, v251
	v_mul_f32_e32 v50, v50, v251
	v_mul_f32_e32 v51, v51, v251
	v_mul_f32_e32 v52, v52, v251
	v_mul_f32_e32 v53, v53, v251
	v_pk_mul_f32 v[62:63], v[62:63], v[130:131]
	v_pk_mul_f32 v[54:55], v[54:55], v[138:139]
	v_pk_mul_f32 v[64:65], v[64:65], v[132:133]
	v_pk_mul_f32 v[56:57], v[56:57], v[140:141]
	v_pk_mul_f32 v[58:59], v[58:59], v[134:135]
	v_pk_mul_f32 v[50:51], v[50:51], v[142:143]
	v_pk_mul_f32 v[60:61], v[60:61], v[136:137]
	v_pk_mul_f32 v[52:53], v[52:53], v[144:145]
	s_waitcnt vmcnt(14)
	v_pk_mul_f32 v[188:189], v[54:55], v[210:211]
	v_pk_mul_f32 v[54:55], v[54:55], v[202:203]
	v_pk_fma_f32 v[202:203], v[62:63], v[202:203], v[188:189] neg_lo:[0,0,1] neg_hi:[0,0,1]
	v_pk_fma_f32 v[210:211], v[62:63], v[210:211], v[54:55]
	v_pk_mul_f32 v[188:189], v[56:57], v[212:213]
	v_pk_mul_f32 v[56:57], v[56:57], v[204:205]
	v_pk_fma_f32 v[204:205], v[64:65], v[204:205], v[188:189] neg_lo:[0,0,1] neg_hi:[0,0,1]
	v_pk_fma_f32 v[212:213], v[64:65], v[212:213], v[56:57]
	v_pk_mul_f32 v[188:189], v[50:51], v[214:215]
	v_pk_mul_f32 v[50:51], v[50:51], v[206:207]
	v_pk_fma_f32 v[206:207], v[58:59], v[206:207], v[188:189] neg_lo:[0,0,1] neg_hi:[0,0,1]
	v_pk_fma_f32 v[214:215], v[58:59], v[214:215], v[50:51]
	v_pk_mul_f32 v[188:189], v[52:53], v[216:217]
	v_pk_mul_f32 v[52:53], v[52:53], v[208:209]
	v_pk_fma_f32 v[208:209], v[60:61], v[208:209], v[188:189] neg_lo:[0,0,1] neg_hi:[0,0,1]
	v_pk_fma_f32 v[216:217], v[60:61], v[216:217], v[52:53]
	s_cmp_eq_u32 s64, 15
	s_cbranch_scc0 .Lk_nof32_k_4
	v_and_b32_e32 v188, 15, v0
	v_lshlrev_b32_e32 v188, 10, v188
	v_lshl_add_u32 v188, v190, 5, v188
	s_add_u32 s62, s96, 0x0
	s_addc_u32 s63, s97, 0
	s_nop 0
	global_store_dwordx4 v188, v[202:205], s[62:63]
	global_store_dwordx4 v188, v[206:209], s[62:63] offset:16
	global_store_dwordx4 v188, v[210:213], s[62:63] offset:128
	global_store_dwordx4 v188, v[214:217], s[62:63] offset:144
.Lk_nof32_k_4:
	v_cvt_pk_bf16_f32 v62, v202, v203
	v_cvt_pk_bf16_f32 v63, v204, v205
	v_cvt_pk_bf16_f32 v64, v206, v207
	v_cvt_pk_bf16_f32 v65, v208, v209
	v_cvt_pk_bf16_f32 v58, v210, v211
	v_cvt_pk_bf16_f32 v59, v212, v213
	v_cvt_pk_bf16_f32 v60, v214, v215
	v_cvt_pk_bf16_f32 v61, v216, v217
	s_add_u32 s62, s58, 0xb000
	s_addc_u32 s63, s59, 0
	s_nop 0
	global_load_dwordx4 v[202:205], v191, s[62:63]
	global_load_dwordx4 v[206:209], v191, s[62:63] offset:16
	global_load_dwordx4 v[210:213], v191, s[62:63] offset:128
	global_load_dwordx4 v[214:217], v191, s[62:63] offset:144
	s_add_u32 s62, s60, 0x10000
	s_addc_u32 s63, s61, 0
	s_nop 0
	global_store_dwordx4 v192, v[62:65], s[62:63]
	global_store_dwordx4 v192, v[58:61], s[62:63] offset:64
	v_mul_f32_e32 v46, v46, v252
	v_mul_f32_e32 v47, v47, v252
	v_mul_f32_e32 v48, v48, v252
	v_mul_f32_e32 v49, v49, v252
	v_mul_f32_e32 v42, v42, v252
	v_mul_f32_e32 v43, v43, v252
	v_mul_f32_e32 v44, v44, v252
	v_mul_f32_e32 v45, v45, v252
	v_mul_f32_e32 v38, v38, v252
	v_mul_f32_e32 v39, v39, v252
	v_mul_f32_e32 v40, v40, v252
	v_mul_f32_e32 v41, v41, v252
	v_mul_f32_e32 v34, v34, v252
	v_mul_f32_e32 v35, v35, v252
	v_mul_f32_e32 v36, v36, v252
	v_mul_f32_e32 v37, v37, v252
	v_pk_mul_f32 v[46:47], v[46:47], v[130:131]
	v_pk_mul_f32 v[38:39], v[38:39], v[138:139]
	v_pk_mul_f32 v[48:49], v[48:49], v[132:133]
	v_pk_mul_f32 v[40:41], v[40:41], v[140:141]
	v_pk_mul_f32 v[42:43], v[42:43], v[134:135]
	v_pk_mul_f32 v[34:35], v[34:35], v[142:143]
	v_pk_mul_f32 v[44:45], v[44:45], v[136:137]
	v_pk_mul_f32 v[36:37], v[36:37], v[144:145]
	s_waitcnt vmcnt(14)
	v_pk_mul_f32 v[188:189], v[38:39], v[226:227]
	v_pk_mul_f32 v[38:39], v[38:39], v[218:219]
	v_pk_fma_f32 v[218:219], v[46:47], v[218:219], v[188:189] neg_lo:[0,0,1] neg_hi:[0,0,1]
	v_pk_fma_f32 v[226:227], v[46:47], v[226:227], v[38:39]
	v_pk_mul_f32 v[188:189], v[40:41], v[228:229]
	v_pk_mul_f32 v[40:41], v[40:41], v[220:221]
	v_pk_fma_f32 v[220:221], v[48:49], v[220:221], v[188:189] neg_lo:[0,0,1] neg_hi:[0,0,1]
	v_pk_fma_f32 v[228:229], v[48:49], v[228:229], v[40:41]
	v_pk_mul_f32 v[188:189], v[34:35], v[162:163]
	v_pk_mul_f32 v[34:35], v[34:35], v[222:223]
	v_pk_fma_f32 v[222:223], v[42:43], v[222:223], v[188:189] neg_lo:[0,0,1] neg_hi:[0,0,1]
	v_pk_fma_f32 v[162:163], v[42:43], v[162:163], v[34:35]
	v_pk_mul_f32 v[188:189], v[36:37], v[164:165]
	v_pk_mul_f32 v[36:37], v[36:37], v[224:225]
	v_pk_fma_f32 v[224:225], v[44:45], v[224:225], v[188:189] neg_lo:[0,0,1] neg_hi:[0,0,1]
	v_pk_fma_f32 v[164:165], v[44:45], v[164:165], v[36:37]
	s_cmp_eq_u32 s64, 15
	s_cbranch_scc0 .Lk_nof32_k_5
	v_and_b32_e32 v188, 15, v0
	v_lshlrev_b32_e32 v188, 10, v188
	v_lshl_add_u32 v188, v190, 5, v188
	s_add_u32 s62, s96, 0x4000
	s_addc_u32 s63, s97, 0
	s_nop 0
	global_store_dwordx4 v188, v[218:221], s[62:63]
	global_store_dwordx4 v188, v[222:225], s[62:63] offset:16
	global_store_dwordx4 v188, v[226:229], s[62:63] offset:128
	global_store_dwordx4 v188, v[162:165], s[62:63] offset:144
.Lk_nof32_k_5:
	v_cvt_pk_bf16_f32 v46, v218, v219
	v_cvt_pk_bf16_f32 v47, v220, v221
	v_cvt_pk_bf16_f32 v48, v222, v223
	v_cvt_pk_bf16_f32 v49, v224, v225
	v_cvt_pk_bf16_f32 v42, v226, v227
	v_cvt_pk_bf16_f32 v43, v228, v229
	v_cvt_pk_bf16_f32 v44, v162, v163
	v_cvt_pk_bf16_f32 v45, v164, v165
	s_add_u32 s62, s60, 0x12000
	s_addc_u32 s63, s61, 0
	s_nop 0
	global_store_dwordx4 v192, v[46:49], s[62:63]
	global_store_dwordx4 v192, v[42:45], s[62:63] offset:64
	v_mul_f32_e32 v30, v30, v253
	v_mul_f32_e32 v31, v31, v253
	v_mul_f32_e32 v32, v32, v253
	v_mul_f32_e32 v33, v33, v253
	v_mul_f32_e32 v26, v26, v253
	v_mul_f32_e32 v27, v27, v253
	v_mul_f32_e32 v28, v28, v253
	v_mul_f32_e32 v29, v29, v253
	v_mul_f32_e32 v22, v22, v253
	v_mul_f32_e32 v23, v23, v253
	v_mul_f32_e32 v24, v24, v253
	v_mul_f32_e32 v25, v25, v253
	v_mul_f32_e32 v18, v18, v253
	v_mul_f32_e32 v19, v19, v253
	v_mul_f32_e32 v20, v20, v253
	v_mul_f32_e32 v21, v21, v253
	v_pk_mul_f32 v[30:31], v[30:31], v[130:131]
	v_pk_mul_f32 v[22:23], v[22:23], v[138:139]
	v_pk_mul_f32 v[32:33], v[32:33], v[132:133]
	v_pk_mul_f32 v[24:25], v[24:25], v[140:141]
	v_pk_mul_f32 v[26:27], v[26:27], v[134:135]
	v_pk_mul_f32 v[18:19], v[18:19], v[142:143]
	v_pk_mul_f32 v[28:29], v[28:29], v[136:137]
	v_pk_mul_f32 v[20:21], v[20:21], v[144:145]
	s_waitcnt vmcnt(10)
	v_pk_mul_f32 v[188:189], v[22:23], v[154:155]
	v_pk_mul_f32 v[22:23], v[22:23], v[146:147]
	v_pk_fma_f32 v[146:147], v[30:31], v[146:147], v[188:189] neg_lo:[0,0,1] neg_hi:[0,0,1]
	v_pk_fma_f32 v[154:155], v[30:31], v[154:155], v[22:23]
	v_pk_mul_f32 v[188:189], v[24:25], v[156:157]
	v_pk_mul_f32 v[24:25], v[24:25], v[148:149]
	v_pk_fma_f32 v[148:149], v[32:33], v[148:149], v[188:189] neg_lo:[0,0,1] neg_hi:[0,0,1]
	v_pk_fma_f32 v[156:157], v[32:33], v[156:157], v[24:25]
	v_pk_mul_f32 v[188:189], v[18:19], v[158:159]
	v_pk_mul_f32 v[18:19], v[18:19], v[150:151]
	v_pk_fma_f32 v[150:151], v[26:27], v[150:151], v[188:189] neg_lo:[0,0,1] neg_hi:[0,0,1]
	v_pk_fma_f32 v[158:159], v[26:27], v[158:159], v[18:19]
	v_pk_mul_f32 v[188:189], v[20:21], v[160:161]
	v_pk_mul_f32 v[20:21], v[20:21], v[152:153]
	v_pk_fma_f32 v[152:153], v[28:29], v[152:153], v[188:189] neg_lo:[0,0,1] neg_hi:[0,0,1]
	v_pk_fma_f32 v[160:161], v[28:29], v[160:161], v[20:21]
	s_cmp_eq_u32 s64, 15
	s_cbranch_scc0 .Lk_nof32_k_6
	v_and_b32_e32 v188, 15, v0
	v_lshlrev_b32_e32 v188, 10, v188
	v_lshl_add_u32 v188, v190, 5, v188
	s_add_u32 s62, s96, 0x8000
	s_addc_u32 s63, s97, 0
	s_nop 0
	global_store_dwordx4 v188, v[146:149], s[62:63]
	global_store_dwordx4 v188, v[150:153], s[62:63] offset:16
	global_store_dwordx4 v188, v[154:157], s[62:63] offset:128
	global_store_dwordx4 v188, v[158:161], s[62:63] offset:144
.Lk_nof32_k_6:
	v_cvt_pk_bf16_f32 v30, v146, v147
	v_cvt_pk_bf16_f32 v31, v148, v149
	v_cvt_pk_bf16_f32 v32, v150, v151
	v_cvt_pk_bf16_f32 v33, v152, v153
	v_cvt_pk_bf16_f32 v26, v154, v155
	v_cvt_pk_bf16_f32 v27, v156, v157
	v_cvt_pk_bf16_f32 v28, v158, v159
	v_cvt_pk_bf16_f32 v29, v160, v161
	s_add_u32 s62, s60, 0x14000
	s_addc_u32 s63, s61, 0
	s_nop 0
	global_store_dwordx4 v192, v[30:33], s[62:63]
	global_store_dwordx4 v192, v[26:29], s[62:63] offset:64
	v_mul_f32_e32 v14, v14, v254
	v_mul_f32_e32 v15, v15, v254
	v_mul_f32_e32 v16, v16, v254
	v_mul_f32_e32 v17, v17, v254
	v_mul_f32_e32 v10, v10, v254
	v_mul_f32_e32 v11, v11, v254
	v_mul_f32_e32 v12, v12, v254
	v_mul_f32_e32 v13, v13, v254
	v_mul_f32_e32 v6, v6, v254
	v_mul_f32_e32 v7, v7, v254
	v_mul_f32_e32 v8, v8, v254
	v_mul_f32_e32 v9, v9, v254
	v_mul_f32_e32 v2, v2, v254
	v_mul_f32_e32 v3, v3, v254
	v_mul_f32_e32 v4, v4, v254
	v_mul_f32_e32 v5, v5, v254
	v_pk_mul_f32 v[14:15], v[14:15], v[130:131]
	v_pk_mul_f32 v[6:7], v[6:7], v[138:139]
	v_pk_mul_f32 v[16:17], v[16:17], v[132:133]
	v_pk_mul_f32 v[8:9], v[8:9], v[140:141]
	v_pk_mul_f32 v[10:11], v[10:11], v[134:135]
	v_pk_mul_f32 v[2:3], v[2:3], v[142:143]
	v_pk_mul_f32 v[12:13], v[12:13], v[136:137]
	v_pk_mul_f32 v[4:5], v[4:5], v[144:145]
	s_waitcnt vmcnt(6)
	v_pk_mul_f32 v[188:189], v[6:7], v[210:211]
	v_pk_mul_f32 v[6:7], v[6:7], v[202:203]
	v_pk_fma_f32 v[202:203], v[14:15], v[202:203], v[188:189] neg_lo:[0,0,1] neg_hi:[0,0,1]
	v_pk_fma_f32 v[210:211], v[14:15], v[210:211], v[6:7]
	v_pk_mul_f32 v[188:189], v[8:9], v[212:213]
	v_pk_mul_f32 v[8:9], v[8:9], v[204:205]
	v_pk_fma_f32 v[204:205], v[16:17], v[204:205], v[188:189] neg_lo:[0,0,1] neg_hi:[0,0,1]
	v_pk_fma_f32 v[212:213], v[16:17], v[212:213], v[8:9]
	v_pk_mul_f32 v[188:189], v[2:3], v[214:215]
	v_pk_mul_f32 v[2:3], v[2:3], v[206:207]
	v_pk_fma_f32 v[206:207], v[10:11], v[206:207], v[188:189] neg_lo:[0,0,1] neg_hi:[0,0,1]
	v_pk_fma_f32 v[214:215], v[10:11], v[214:215], v[2:3]
	v_pk_mul_f32 v[188:189], v[4:5], v[216:217]
	v_pk_mul_f32 v[4:5], v[4:5], v[208:209]
	v_pk_fma_f32 v[208:209], v[12:13], v[208:209], v[188:189] neg_lo:[0,0,1] neg_hi:[0,0,1]
	v_pk_fma_f32 v[216:217], v[12:13], v[216:217], v[4:5]
	s_cmp_eq_u32 s64, 15
	s_cbranch_scc0 .Lk_nof32_k_7
	v_and_b32_e32 v188, 15, v0
	v_lshlrev_b32_e32 v188, 10, v188
	v_lshl_add_u32 v188, v190, 5, v188
	s_add_u32 s62, s96, 0xc000
	s_addc_u32 s63, s97, 0
	s_nop 0
	global_store_dwordx4 v188, v[202:205], s[62:63]
	global_store_dwordx4 v188, v[206:209], s[62:63] offset:16
	global_store_dwordx4 v188, v[210:213], s[62:63] offset:128
	global_store_dwordx4 v188, v[214:217], s[62:63] offset:144
.Lk_nof32_k_7:
	v_cvt_pk_bf16_f32 v14, v202, v203
	v_cvt_pk_bf16_f32 v15, v204, v205
	v_cvt_pk_bf16_f32 v16, v206, v207
	v_cvt_pk_bf16_f32 v17, v208, v209
	v_cvt_pk_bf16_f32 v10, v210, v211
	v_cvt_pk_bf16_f32 v11, v212, v213
	v_cvt_pk_bf16_f32 v12, v214, v215
	v_cvt_pk_bf16_f32 v13, v216, v217
	s_add_u32 s62, s60, 0x16000
	s_addc_u32 s63, s61, 0
	s_nop 0
	global_store_dwordx4 v192, v[14:17], s[62:63]
	global_store_dwordx4 v192, v[10:13], s[62:63] offset:64
	s_branch .LBB0_635
.LBB0_654:
	v_lshrrev_b32_e32 v190, 6, v0
	v_and_b32_e32 v192, 15, v0
	v_readfirstlane_b32 s98, v190
	v_bfe_u32 v190, v0, 4, 2
	s_lshl_b32 s100, s24, 8
	s_and_b32 s99, s98, 3
	s_lshr_b32 s98, s98, 2
	s_lshl_b32 s101, s98, 6
	s_add_i32 s100, s100, s101
	v_add_u32_e32 v188, s100, v192
	v_lshlrev_b32_e32 v189, 7, v188
	v_lshl_add_u32 v189, v190, 4, v189
	s_add_u32 s58, s6, 0x10900000
	s_addc_u32 s59, s7, 0
	s_nop 0
	global_load_dwordx4 v[202:205], v189, s[58:59]
	global_load_dwordx4 v[206:209], v189, s[58:59] offset:2048
	s_add_u32 s62, s58, 0x1000
	s_addc_u32 s63, s59, 0
	s_nop 0
	global_load_dwordx4 v[210:213], v189, s[62:63]
	s_add_u32 s62, s58, 0x1800
	s_addc_u32 s63, s59, 0
	s_nop 0
	global_load_dwordx4 v[214:217], v189, s[62:63]
	s_add_u32 s62, s58, 0x4000
	s_addc_u32 s63, s59, 0
	s_nop 0
	global_load_dwordx4 v[218:221], v189, s[62:63]
	s_add_u32 s62, s58, 0x4800
	s_addc_u32 s63, s59, 0
	s_nop 0
	global_load_dwordx4 v[222:225], v189, s[62:63]
	s_add_u32 s62, s58, 0x5000
	s_addc_u32 s63, s59, 0
	s_nop 0
	global_load_dwordx4 v[226:229], v189, s[62:63]
	s_add_u32 s62, s58, 0x5800
	s_addc_u32 s63, s59, 0
	s_nop 0
	global_load_dwordx4 v[162:165], v189, s[62:63]
	s_lshl_b32 s100, s99, 6
	v_lshlrev_b32_e32 v192, 9, v188
	v_add_u32_e32 v192, s100, v192
	v_lshl_add_u32 v192, v190, 4, v192
	s_add_u32 s60, s6, 0x8100000
	s_addc_u32 s61, s7, 0
	v_mov_b32_e32 v193, 0x200e0
	ds_read_b64 v[188:189], v193
	v_and_b32_e32 v191, 15, v0
	v_lshlrev_b32_e32 v191, 10, v191
	v_lshl_add_u32 v191, v190, 5, v191
	s_and_b32 s64, s24, 15
	s_lshr_b32 s65, s24, 4
	s_lshl_b32 s65, s65, 7
	s_lshl_b32 s100, s98, 6
	s_add_i32 s65, s65, s100
	s_lshl_b32 s65, s65, 10
	s_lshl_b32 s100, s99, 7
	s_add_i32 s65, s65, s100
	s_add_i32 s65, s65, 0x4140000
	s_waitcnt lgkmcnt(0)
	v_readfirstlane_b32 s96, v188
	v_readfirstlane_b32 s97, v189
	s_nop 3
	s_add_u32 s96, s96, s65
	s_addc_u32 s97, s97, 0
	v_and_b32_e32 v193, 63, v0
	v_xor_b32_e32 v194, 32, v193
	v_xor_b32_e32 v193, 16, v193
	v_lshlrev_b32_e32 v193, 2, v193
	v_lshlrev_b32_e32 v194, 2, v194
	v_mov_b32_e32 v188, 0x3a800000
	s_waitcnt vmcnt(0)
	v_add_f32_e32 v202, v202, v203
	v_add_f32_e32 v204, v204, v205
	v_add_f32_e32 v202, v202, v204
	v_add_f32_e32 v206, v206, v207
	v_add_f32_e32 v208, v208, v209
	v_add_f32_e32 v206, v206, v208
	v_add_f32_e32 v210, v210, v211
	v_add_f32_e32 v212, v212, v213
	v_add_f32_e32 v210, v210, v212
	v_add_f32_e32 v214, v214, v215
	v_add_f32_e32 v216, v216, v217
	v_add_f32_e32 v214, v214, v216
	v_add_f32_e32 v218, v218, v219
	v_add_f32_e32 v220, v220, v221
	v_add_f32_e32 v218, v218, v220
	v_add_f32_e32 v222, v222, v223
	v_add_f32_e32 v224, v224, v225
	v_add_f32_e32 v222, v222, v224
	v_add_f32_e32 v226, v226, v227
	v_add_f32_e32 v228, v228, v229
	v_add_f32_e32 v226, v226, v228
	v_add_f32_e32 v162, v162, v163
	v_add_f32_e32 v164, v164, v165
	v_add_f32_e32 v162, v162, v164
	ds_bpermute_b32 v203, v193, v202
	ds_bpermute_b32 v207, v193, v206
	ds_bpermute_b32 v211, v193, v210
	ds_bpermute_b32 v215, v193, v214
	ds_bpermute_b32 v219, v193, v218
	ds_bpermute_b32 v223, v193, v222
	ds_bpermute_b32 v227, v193, v226
	ds_bpermute_b32 v163, v193, v162
	s_waitcnt lgkmcnt(7)
	v_add_f32_e32 v202, v202, v203
	s_waitcnt lgkmcnt(6)
	v_add_f32_e32 v206, v206, v207
	s_waitcnt lgkmcnt(5)
	v_add_f32_e32 v210, v210, v211
	s_waitcnt lgkmcnt(4)
	v_add_f32_e32 v214, v214, v215
	s_waitcnt lgkmcnt(3)
	v_add_f32_e32 v218, v218, v219
	s_waitcnt lgkmcnt(2)
	v_add_f32_e32 v222, v222, v223
	s_waitcnt lgkmcnt(1)
	v_add_f32_e32 v226, v226, v227
	s_waitcnt lgkmcnt(0)
	v_add_f32_e32 v162, v162, v163
	ds_bpermute_b32 v203, v194, v202
	ds_bpermute_b32 v207, v194, v206
	ds_bpermute_b32 v211, v194, v210
	ds_bpermute_b32 v215, v194, v214
	ds_bpermute_b32 v219, v194, v218
	ds_bpermute_b32 v223, v194, v222
	ds_bpermute_b32 v227, v194, v226
	ds_bpermute_b32 v163, v194, v162
	s_waitcnt lgkmcnt(7)
	v_add_f32_e32 v202, v202, v203
	s_waitcnt lgkmcnt(6)
	v_add_f32_e32 v206, v206, v207
	s_waitcnt lgkmcnt(5)
	v_add_f32_e32 v210, v210, v211
	s_waitcnt lgkmcnt(4)
	v_add_f32_e32 v214, v214, v215
	s_waitcnt lgkmcnt(3)
	v_add_f32_e32 v218, v218, v219
	s_waitcnt lgkmcnt(2)
	v_add_f32_e32 v222, v222, v223
	s_waitcnt lgkmcnt(1)
	v_add_f32_e32 v226, v226, v227
	s_waitcnt lgkmcnt(0)
	v_add_f32_e32 v162, v162, v163
	v_fmaak_f32 v202, v188, v202, 0x358637bd
	v_rsq_f32_e32 v230, v202
	v_fmaak_f32 v206, v188, v206, 0x358637bd
	v_rsq_f32_e32 v248, v206
	v_fmaak_f32 v210, v188, v210, 0x358637bd
	v_rsq_f32_e32 v249, v210
	v_fmaak_f32 v214, v188, v214, 0x358637bd
	v_rsq_f32_e32 v250, v214
	v_fmaak_f32 v218, v188, v218, 0x358637bd
	v_rsq_f32_e32 v251, v218
	v_fmaak_f32 v222, v188, v222, 0x358637bd
	v_rsq_f32_e32 v252, v222
	v_fmaak_f32 v226, v188, v226, 0x358637bd
	v_rsq_f32_e32 v253, v226
	v_fmaak_f32 v162, v188, v162, 0x358637bd
	v_rsq_f32_e32 v254, v162
	s_nop 0
	v_mul_f32_e32 v126, v126, v230
	v_mul_f32_e32 v127, v127, v230
	v_mul_f32_e32 v128, v128, v230
	v_mul_f32_e32 v129, v129, v230
	v_mul_f32_e32 v122, v122, v230
	v_mul_f32_e32 v123, v123, v230
	v_mul_f32_e32 v124, v124, v230
	v_mul_f32_e32 v125, v125, v230
	v_mul_f32_e32 v118, v118, v230
	v_mul_f32_e32 v119, v119, v230
	v_mul_f32_e32 v120, v120, v230
	v_mul_f32_e32 v121, v121, v230
	v_mul_f32_e32 v114, v114, v230
	v_mul_f32_e32 v115, v115, v230
	v_mul_f32_e32 v116, v116, v230
	v_mul_f32_e32 v117, v117, v230
	v_cvt_pk_bf16_f32 v126, v126, v127
	v_cvt_pk_bf16_f32 v127, v128, v129
	v_cvt_pk_bf16_f32 v128, v122, v123
	v_cvt_pk_bf16_f32 v129, v124, v125
	global_store_dwordx4 v192, v[126:129], s[60:61]
	v_cvt_pk_bf16_f32 v118, v118, v119
	v_cvt_pk_bf16_f32 v119, v120, v121
	v_cvt_pk_bf16_f32 v120, v114, v115
	v_cvt_pk_bf16_f32 v121, v116, v117
	global_store_dwordx4 v192, v[118:121], s[60:61] offset:256
	s_add_u32 s62, s60, 0x2000
	s_addc_u32 s63, s61, 0
	v_mul_f32_e32 v110, v110, v248
	v_mul_f32_e32 v111, v111, v248
	v_mul_f32_e32 v112, v112, v248
	v_mul_f32_e32 v113, v113, v248
	v_mul_f32_e32 v106, v106, v248
	v_mul_f32_e32 v107, v107, v248
	v_mul_f32_e32 v108, v108, v248
	v_mul_f32_e32 v109, v109, v248
	v_mul_f32_e32 v102, v102, v248
	v_mul_f32_e32 v103, v103, v248
	v_mul_f32_e32 v104, v104, v248
	v_mul_f32_e32 v105, v105, v248
	v_mul_f32_e32 v98, v98, v248
	v_mul_f32_e32 v99, v99, v248
	v_mul_f32_e32 v100, v100, v248
	v_mul_f32_e32 v101, v101, v248
	v_cvt_pk_bf16_f32 v110, v110, v111
	v_cvt_pk_bf16_f32 v111, v112, v113
	v_cvt_pk_bf16_f32 v112, v106, v107
	v_cvt_pk_bf16_f32 v113, v108, v109
	global_store_dwordx4 v192, v[110:113], s[62:63]
	v_cvt_pk_bf16_f32 v102, v102, v103
	v_cvt_pk_bf16_f32 v103, v104, v105
	v_cvt_pk_bf16_f32 v104, v98, v99
	v_cvt_pk_bf16_f32 v105, v100, v101
	global_store_dwordx4 v192, v[102:105], s[62:63] offset:256
	s_add_u32 s62, s60, 0x4000
	s_addc_u32 s63, s61, 0
	v_mul_f32_e32 v94, v94, v249
	v_mul_f32_e32 v95, v95, v249
	v_mul_f32_e32 v96, v96, v249
	v_mul_f32_e32 v97, v97, v249
	v_mul_f32_e32 v90, v90, v249
	v_mul_f32_e32 v91, v91, v249
	v_mul_f32_e32 v92, v92, v249
	v_mul_f32_e32 v93, v93, v249
	v_mul_f32_e32 v86, v86, v249
	v_mul_f32_e32 v87, v87, v249
	v_mul_f32_e32 v88, v88, v249
	v_mul_f32_e32 v89, v89, v249
	v_mul_f32_e32 v82, v82, v249
	v_mul_f32_e32 v83, v83, v249
	v_mul_f32_e32 v84, v84, v249
	v_mul_f32_e32 v85, v85, v249
	v_cvt_pk_bf16_f32 v94, v94, v95
	v_cvt_pk_bf16_f32 v95, v96, v97
	v_cvt_pk_bf16_f32 v96, v90, v91
	v_cvt_pk_bf16_f32 v97, v92, v93
	global_store_dwordx4 v192, v[94:97], s[62:63]
	v_cvt_pk_bf16_f32 v86, v86, v87
	v_cvt_pk_bf16_f32 v87, v88, v89
	v_cvt_pk_bf16_f32 v88, v82, v83
	v_cvt_pk_bf16_f32 v89, v84, v85
	global_store_dwordx4 v192, v[86:89], s[62:63] offset:256
	s_add_u32 s62, s60, 0x6000
	s_addc_u32 s63, s61, 0
	v_mul_f32_e32 v78, v78, v250
	v_mul_f32_e32 v79, v79, v250
	v_mul_f32_e32 v80, v80, v250
	v_mul_f32_e32 v81, v81, v250
	v_mul_f32_e32 v74, v74, v250
	v_mul_f32_e32 v75, v75, v250
	v_mul_f32_e32 v76, v76, v250
	v_mul_f32_e32 v77, v77, v250
	v_mul_f32_e32 v70, v70, v250
	v_mul_f32_e32 v71, v71, v250
	v_mul_f32_e32 v72, v72, v250
	v_mul_f32_e32 v73, v73, v250
	v_mul_f32_e32 v66, v66, v250
	v_mul_f32_e32 v67, v67, v250
	v_mul_f32_e32 v68, v68, v250
	v_mul_f32_e32 v69, v69, v250
	v_cvt_pk_bf16_f32 v78, v78, v79
	v_cvt_pk_bf16_f32 v79, v80, v81
	v_cvt_pk_bf16_f32 v80, v74, v75
	v_cvt_pk_bf16_f32 v81, v76, v77
	global_store_dwordx4 v192, v[78:81], s[62:63]
	v_cvt_pk_bf16_f32 v70, v70, v71
	v_cvt_pk_bf16_f32 v71, v72, v73
	v_cvt_pk_bf16_f32 v72, v66, v67
	v_cvt_pk_bf16_f32 v73, v68, v69
	global_store_dwordx4 v192, v[70:73], s[62:63] offset:256
	s_add_u32 s62, s60, 0x10000
	s_addc_u32 s63, s61, 0
	v_mul_f32_e32 v62, v62, v251
	v_mul_f32_e32 v63, v63, v251
	v_mul_f32_e32 v64, v64, v251
	v_mul_f32_e32 v65, v65, v251
	v_mul_f32_e32 v58, v58, v251
	v_mul_f32_e32 v59, v59, v251
	v_mul_f32_e32 v60, v60, v251
	v_mul_f32_e32 v61, v61, v251
	v_mul_f32_e32 v54, v54, v251
	v_mul_f32_e32 v55, v55, v251
	v_mul_f32_e32 v56, v56, v251
	v_mul_f32_e32 v57, v57, v251
	v_mul_f32_e32 v50, v50, v251
	v_mul_f32_e32 v51, v51, v251
	v_mul_f32_e32 v52, v52, v251
	v_mul_f32_e32 v53, v53, v251
	s_cmp_eq_u32 s64, 15
	s_cbranch_scc0 .Lv_nof32_v_4
	s_add_u32 s100, s96, 0x0
	s_addc_u32 s101, s97, 0
	s_nop 0
	global_store_dwordx4 v191, v[62:65], s[100:101]
	global_store_dwordx4 v191, v[58:61], s[100:101] offset:16
	global_store_dwordx4 v191, v[54:57], s[100:101] offset:512
	global_store_dwordx4 v191, v[50:53], s[100:101] offset:528
	s_nop 1
.Lv_nof32_v_4:
	v_cvt_pk_bf16_f32 v62, v62, v63
	v_cvt_pk_bf16_f32 v63, v64, v65
	v_cvt_pk_bf16_f32 v64, v58, v59
	v_cvt_pk_bf16_f32 v65, v60, v61
	global_store_dwordx4 v192, v[62:65], s[62:63]
	v_cvt_pk_bf16_f32 v54, v54, v55
	v_cvt_pk_bf16_f32 v55, v56, v57
	v_cvt_pk_bf16_f32 v56, v50, v51
	v_cvt_pk_bf16_f32 v57, v52, v53
	global_store_dwordx4 v192, v[54:57], s[62:63] offset:256
	s_add_u32 s62, s60, 0x12000
	s_addc_u32 s63, s61, 0
	v_mul_f32_e32 v46, v46, v252
	v_mul_f32_e32 v47, v47, v252
	v_mul_f32_e32 v48, v48, v252
	v_mul_f32_e32 v49, v49, v252
	v_mul_f32_e32 v42, v42, v252
	v_mul_f32_e32 v43, v43, v252
	v_mul_f32_e32 v44, v44, v252
	v_mul_f32_e32 v45, v45, v252
	v_mul_f32_e32 v38, v38, v252
	v_mul_f32_e32 v39, v39, v252
	v_mul_f32_e32 v40, v40, v252
	v_mul_f32_e32 v41, v41, v252
	v_mul_f32_e32 v34, v34, v252
	v_mul_f32_e32 v35, v35, v252
	v_mul_f32_e32 v36, v36, v252
	v_mul_f32_e32 v37, v37, v252
	s_cmp_eq_u32 s64, 15
	s_cbranch_scc0 .Lv_nof32_v_5
	s_add_u32 s100, s96, 0x4000
	s_addc_u32 s101, s97, 0
	s_nop 0
	global_store_dwordx4 v191, v[46:49], s[100:101]
	global_store_dwordx4 v191, v[42:45], s[100:101] offset:16
	global_store_dwordx4 v191, v[38:41], s[100:101] offset:512
	global_store_dwordx4 v191, v[34:37], s[100:101] offset:528
	s_nop 1
.Lv_nof32_v_5:
	v_cvt_pk_bf16_f32 v46, v46, v47
	v_cvt_pk_bf16_f32 v47, v48, v49
	v_cvt_pk_bf16_f32 v48, v42, v43
	v_cvt_pk_bf16_f32 v49, v44, v45
	global_store_dwordx4 v192, v[46:49], s[62:63]
	v_cvt_pk_bf16_f32 v38, v38, v39
	v_cvt_pk_bf16_f32 v39, v40, v41
	v_cvt_pk_bf16_f32 v40, v34, v35
	v_cvt_pk_bf16_f32 v41, v36, v37
	global_store_dwordx4 v192, v[38:41], s[62:63] offset:256
	s_add_u32 s62, s60, 0x14000
	s_addc_u32 s63, s61, 0
	v_mul_f32_e32 v30, v30, v253
	v_mul_f32_e32 v31, v31, v253
	v_mul_f32_e32 v32, v32, v253
	v_mul_f32_e32 v33, v33, v253
	v_mul_f32_e32 v26, v26, v253
	v_mul_f32_e32 v27, v27, v253
	v_mul_f32_e32 v28, v28, v253
	v_mul_f32_e32 v29, v29, v253
	v_mul_f32_e32 v22, v22, v253
	v_mul_f32_e32 v23, v23, v253
	v_mul_f32_e32 v24, v24, v253
	v_mul_f32_e32 v25, v25, v253
	v_mul_f32_e32 v18, v18, v253
	v_mul_f32_e32 v19, v19, v253
	v_mul_f32_e32 v20, v20, v253
	v_mul_f32_e32 v21, v21, v253
	s_cmp_eq_u32 s64, 15
	s_cbranch_scc0 .Lv_nof32_v_6
	s_add_u32 s100, s96, 0x8000
	s_addc_u32 s101, s97, 0
	s_nop 0
	global_store_dwordx4 v191, v[30:33], s[100:101]
	global_store_dwordx4 v191, v[26:29], s[100:101] offset:16
	global_store_dwordx4 v191, v[22:25], s[100:101] offset:512
	global_store_dwordx4 v191, v[18:21], s[100:101] offset:528
	s_nop 1
.Lv_nof32_v_6:
	v_cvt_pk_bf16_f32 v30, v30, v31
	v_cvt_pk_bf16_f32 v31, v32, v33
	v_cvt_pk_bf16_f32 v32, v26, v27
	v_cvt_pk_bf16_f32 v33, v28, v29
	global_store_dwordx4 v192, v[30:33], s[62:63]
	v_cvt_pk_bf16_f32 v22, v22, v23
	v_cvt_pk_bf16_f32 v23, v24, v25
	v_cvt_pk_bf16_f32 v24, v18, v19
	v_cvt_pk_bf16_f32 v25, v20, v21
	global_store_dwordx4 v192, v[22:25], s[62:63] offset:256
	s_add_u32 s62, s60, 0x16000
	s_addc_u32 s63, s61, 0
	v_mul_f32_e32 v14, v14, v254
	v_mul_f32_e32 v15, v15, v254
	v_mul_f32_e32 v16, v16, v254
	v_mul_f32_e32 v17, v17, v254
	v_mul_f32_e32 v10, v10, v254
	v_mul_f32_e32 v11, v11, v254
	v_mul_f32_e32 v12, v12, v254
	v_mul_f32_e32 v13, v13, v254
	v_mul_f32_e32 v6, v6, v254
	v_mul_f32_e32 v7, v7, v254
	v_mul_f32_e32 v8, v8, v254
	v_mul_f32_e32 v9, v9, v254
	v_mul_f32_e32 v2, v2, v254
	v_mul_f32_e32 v3, v3, v254
	v_mul_f32_e32 v4, v4, v254
	v_mul_f32_e32 v5, v5, v254
	s_cmp_eq_u32 s64, 15
	s_cbranch_scc0 .Lv_nof32_v_7
	s_add_u32 s100, s96, 0xc000
	s_addc_u32 s101, s97, 0
	s_nop 0
	global_store_dwordx4 v191, v[14:17], s[100:101]
	global_store_dwordx4 v191, v[10:13], s[100:101] offset:16
	global_store_dwordx4 v191, v[6:9], s[100:101] offset:512
	global_store_dwordx4 v191, v[2:5], s[100:101] offset:528
	s_nop 1
.Lv_nof32_v_7:
	v_cvt_pk_bf16_f32 v14, v14, v15
	v_cvt_pk_bf16_f32 v15, v16, v17
	v_cvt_pk_bf16_f32 v16, v10, v11
	v_cvt_pk_bf16_f32 v17, v12, v13
	global_store_dwordx4 v192, v[14:17], s[62:63]
	v_cvt_pk_bf16_f32 v6, v6, v7
	v_cvt_pk_bf16_f32 v7, v8, v9
	v_cvt_pk_bf16_f32 v8, v2, v3
	v_cvt_pk_bf16_f32 v9, v4, v5
	global_store_dwordx4 v192, v[6:9], s[62:63] offset:256
	s_branch .LBB0_635
